# stack + K-loop priority raise moved before the opening barrier / drop after the closing barrier (pure MFMA segment)
# speedup vs baseline: 1.0027x; 1.0027x over previous
.LBB0_228:
	ds_read_b128 v[128:131], v179
	ds_read_b128 v[132:135], v179 offset:1024
	ds_read_b128 v[136:139], v179 offset:2048
	ds_read_b128 v[140:143], v179 offset:3072
	ds_read_b128 v[162:165], v180
	ds_read_b128 v[166:169], v180 offset:1024
	ds_read_b128 v[170:173], v180 offset:2048
	ds_read_b128 v[186:189], v180 offset:3072
	s_add_u32 s8, s6, 0x10000
	s_addc_u32 s9, s7, 0
	s_cmp_eq_u32 s92, 12
	s_cselect_b32 s80, s69, s8
	s_cselect_b32 s81, s18, s9
	s_cselect_b32 s12, s77, vcc_lo
	s_cselect_b32 s13, s71, vcc_hi
	s_add_u32 s10, s80, 0x8000
	s_addc_u32 s11, s81, 0
	s_add_i32 m0, s79, 0xc000
	ds_read_b128 v[190:193], v181
	ds_read_b128 v[194:197], v181 offset:1024
	ds_read_b128 v[198:201], v181 offset:2048
	ds_read_b128 v[202:205], v181 offset:3072
	ds_read_b128 v[206:209], v181 offset:4096
	ds_read_b128 v[210:213], v181 offset:5120
	ds_read_b128 v[214:217], v181 offset:6144
	ds_read_b128 v[218:221], v181 offset:7168
	global_load_lds_dwordx4 v154, s[6:7]
	s_add_i32 m0, s79, 0xe000
	s_nop 0
	global_load_lds_dwordx4 v156, s[6:7]
	s_waitcnt vmcnt(8)
	s_waitcnt lgkmcnt(0)
	s_setprio 1
	s_barrier
	v_mfma_f32_16x16x32_bf16 v[124:127], v[128:131], v[190:193], v[124:127]
	v_mfma_f32_16x16x32_bf16 v[120:123], v[136:139], v[190:193], v[120:123]
	v_mfma_f32_16x16x32_bf16 v[108:111], v[128:131], v[198:201], v[108:111]
	v_mfma_f32_16x16x32_bf16 v[104:107], v[136:139], v[198:201], v[104:107]
	v_mfma_f32_16x16x32_bf16 v[92:95], v[128:131], v[206:209], v[92:95]
	v_mfma_f32_16x16x32_bf16 v[88:91], v[136:139], v[206:209], v[88:91]
	v_mfma_f32_16x16x32_bf16 v[76:79], v[128:131], v[214:217], v[76:79]
	v_mfma_f32_16x16x32_bf16 v[72:75], v[136:139], v[214:217], v[72:75]
	v_mfma_f32_16x16x32_bf16 v[124:127], v[132:135], v[194:197], v[124:127]
	v_mfma_f32_16x16x32_bf16 v[120:123], v[140:143], v[194:197], v[120:123]
	v_mfma_f32_16x16x32_bf16 v[108:111], v[132:135], v[202:205], v[108:111]
	v_mfma_f32_16x16x32_bf16 v[104:107], v[140:143], v[202:205], v[104:107]
	v_mfma_f32_16x16x32_bf16 v[92:95], v[132:135], v[210:213], v[92:95]
	v_mfma_f32_16x16x32_bf16 v[88:91], v[140:143], v[210:213], v[88:91]
	v_mfma_f32_16x16x32_bf16 v[76:79], v[132:135], v[218:221], v[76:79]
	v_mfma_f32_16x16x32_bf16 v[72:75], v[140:143], v[218:221], v[72:75]
	v_mfma_f32_16x16x32_bf16 v[116:119], v[162:165], v[190:193], v[116:119]
	v_mfma_f32_16x16x32_bf16 v[112:115], v[170:173], v[190:193], v[112:115]
	v_mfma_f32_16x16x32_bf16 v[100:103], v[162:165], v[198:201], v[100:103]
	v_mfma_f32_16x16x32_bf16 v[96:99], v[170:173], v[198:201], v[96:99]
	v_mfma_f32_16x16x32_bf16 v[84:87], v[162:165], v[206:209], v[84:87]
	v_mfma_f32_16x16x32_bf16 v[80:83], v[170:173], v[206:209], v[80:83]
	v_mfma_f32_16x16x32_bf16 v[68:71], v[162:165], v[214:217], v[68:71]
	v_mfma_f32_16x16x32_bf16 v[64:67], v[170:173], v[214:217], v[64:67]
	v_mfma_f32_16x16x32_bf16 v[116:119], v[166:169], v[194:197], v[116:119]
	v_mfma_f32_16x16x32_bf16 v[112:115], v[186:189], v[194:197], v[112:115]
	v_mfma_f32_16x16x32_bf16 v[100:103], v[166:169], v[202:205], v[100:103]
	v_mfma_f32_16x16x32_bf16 v[96:99], v[186:189], v[202:205], v[96:99]
	v_mfma_f32_16x16x32_bf16 v[84:87], v[166:169], v[210:213], v[84:87]
	v_mfma_f32_16x16x32_bf16 v[80:83], v[186:189], v[210:213], v[80:83]
	v_mfma_f32_16x16x32_bf16 v[68:71], v[166:169], v[218:221], v[68:71]
	v_mfma_f32_16x16x32_bf16 v[64:67], v[186:189], v[218:221], v[64:67]
	s_barrier
	s_setprio 0
	s_add_i32 s6, s34, s84
	s_mov_b32 m0, s6
	ds_read_b128 v[190:193], v181 offset:16384
	ds_read_b128 v[194:197], v181 offset:17408
	ds_read_b128 v[198:201], v181 offset:18432
	ds_read_b128 v[202:205], v181 offset:19456
	ds_read_b128 v[206:209], v181 offset:20480
	ds_read_b128 v[210:213], v181 offset:21504
	ds_read_b128 v[214:217], v181 offset:22528
	ds_read_b128 v[218:221], v181 offset:23552
	global_load_lds_dwordx4 v146, s[12:13]
	s_add_i32 m0, s6, 0x2000
	s_add_u32 s6, s12, 0x40000
	s_addc_u32 s7, s13, 0
	s_add_i32 s38, s35, s84
	global_load_lds_dwordx4 v150, s[12:13]
	s_mov_b32 m0, s38
	s_nop 0
	global_load_lds_dwordx4 v146, s[6:7]
	s_add_i32 m0, s38, 0x2000
	s_nop 0
	global_load_lds_dwordx4 v150, s[6:7]
	s_mov_b32 m0, s79
	s_nop 0
	global_load_lds_dwordx4 v144, s[80:81]
	s_mov_b32 m0, s85
	s_nop 0
	global_load_lds_dwordx4 v148, s[80:81]
	s_waitcnt vmcnt(8)
	s_waitcnt lgkmcnt(0)
	s_setprio 1
	s_barrier
	v_mfma_f32_16x16x32_bf16 v[60:63], v[128:131], v[190:193], v[60:63]
	v_mfma_f32_16x16x32_bf16 v[56:59], v[136:139], v[190:193], v[56:59]
	v_mfma_f32_16x16x32_bf16 v[44:47], v[128:131], v[198:201], v[44:47]
	v_mfma_f32_16x16x32_bf16 v[40:43], v[136:139], v[198:201], v[40:43]
	v_mfma_f32_16x16x32_bf16 v[28:31], v[128:131], v[206:209], v[28:31]
	v_mfma_f32_16x16x32_bf16 v[24:27], v[136:139], v[206:209], v[24:27]
	v_mfma_f32_16x16x32_bf16 v[12:15], v[128:131], v[214:217], v[12:15]
	v_mfma_f32_16x16x32_bf16 v[8:11], v[136:139], v[214:217], v[8:11]
	v_mfma_f32_16x16x32_bf16 v[60:63], v[132:135], v[194:197], v[60:63]
	v_mfma_f32_16x16x32_bf16 v[56:59], v[140:143], v[194:197], v[56:59]
	v_mfma_f32_16x16x32_bf16 v[44:47], v[132:135], v[202:205], v[44:47]
	v_mfma_f32_16x16x32_bf16 v[40:43], v[140:143], v[202:205], v[40:43]
	v_mfma_f32_16x16x32_bf16 v[28:31], v[132:135], v[210:213], v[28:31]
	v_mfma_f32_16x16x32_bf16 v[24:27], v[140:143], v[210:213], v[24:27]
	v_mfma_f32_16x16x32_bf16 v[12:15], v[132:135], v[218:221], v[12:15]
	v_mfma_f32_16x16x32_bf16 v[8:11], v[140:143], v[218:221], v[8:11]
	v_mfma_f32_16x16x32_bf16 v[52:55], v[162:165], v[190:193], v[52:55]
	v_mfma_f32_16x16x32_bf16 v[48:51], v[170:173], v[190:193], v[48:51]
	v_mfma_f32_16x16x32_bf16 v[36:39], v[162:165], v[198:201], v[36:39]
	v_mfma_f32_16x16x32_bf16 v[32:35], v[170:173], v[198:201], v[32:35]
	v_mfma_f32_16x16x32_bf16 v[20:23], v[162:165], v[206:209], v[20:23]
	v_mfma_f32_16x16x32_bf16 v[16:19], v[170:173], v[206:209], v[16:19]
	v_mfma_f32_16x16x32_bf16 v[4:7], v[162:165], v[214:217], v[4:7]
	v_mfma_f32_16x16x32_bf16 v[0:3], v[170:173], v[214:217], v[0:3]
	v_mfma_f32_16x16x32_bf16 v[52:55], v[166:169], v[194:197], v[52:55]
	v_mfma_f32_16x16x32_bf16 v[48:51], v[186:189], v[194:197], v[48:51]
	v_mfma_f32_16x16x32_bf16 v[36:39], v[166:169], v[202:205], v[36:39]
	v_mfma_f32_16x16x32_bf16 v[32:35], v[186:189], v[202:205], v[32:35]
	v_mfma_f32_16x16x32_bf16 v[20:23], v[166:169], v[210:213], v[20:23]
	v_mfma_f32_16x16x32_bf16 v[16:19], v[186:189], v[210:213], v[16:19]
	v_mfma_f32_16x16x32_bf16 v[4:7], v[166:169], v[218:221], v[4:7]
	v_mfma_f32_16x16x32_bf16 v[0:3], v[186:189], v[218:221], v[0:3]
	s_barrier
	s_setprio 0
	s_add_i32 s38, 0, 0x18000
	s_add_i32 s39, 0, 0x1c000
	v_add_u32_e32 v140, s38, v178
	v_add_u32_e32 v152, s39, v178
	ds_read_b128 v[128:131], v140
	ds_read_b128 v[132:135], v140 offset:1024
	ds_read_b128 v[136:139], v140 offset:2048
	ds_read_b128 v[140:143], v140 offset:3072
	ds_read_b128 v[162:165], v152
	ds_read_b128 v[166:169], v152 offset:1024
	ds_read_b128 v[170:173], v152 offset:2048
	ds_read_b128 v[186:189], v152 offset:3072
	s_add_u32 s6, s80, 0x4000
	s_addc_u32 s7, s81, 0
	s_mov_b32 m0, s86
	ds_read_b128 v[190:193], v181 offset:32768
	ds_read_b128 v[194:197], v181 offset:33792
	ds_read_b128 v[198:201], v181 offset:34816
	ds_read_b128 v[202:205], v181 offset:35840
	ds_read_b128 v[206:209], v181 offset:36864
	ds_read_b128 v[210:213], v181 offset:37888
	ds_read_b128 v[214:217], v181 offset:38912
	ds_read_b128 v[218:221], v181 offset:39936
	global_load_lds_dwordx4 v144, s[6:7]
	s_mov_b32 m0, s87
	s_nop 0
	global_load_lds_dwordx4 v148, s[6:7]
	s_waitcnt vmcnt(8)
	s_waitcnt lgkmcnt(0)
	s_setprio 1
	s_barrier
	v_mfma_f32_16x16x32_bf16 v[124:127], v[128:131], v[190:193], v[124:127]
	v_mfma_f32_16x16x32_bf16 v[120:123], v[136:139], v[190:193], v[120:123]
	v_mfma_f32_16x16x32_bf16 v[108:111], v[128:131], v[198:201], v[108:111]
	v_mfma_f32_16x16x32_bf16 v[104:107], v[136:139], v[198:201], v[104:107]
	v_mfma_f32_16x16x32_bf16 v[92:95], v[128:131], v[206:209], v[92:95]
	v_mfma_f32_16x16x32_bf16 v[88:91], v[136:139], v[206:209], v[88:91]
	v_mfma_f32_16x16x32_bf16 v[76:79], v[128:131], v[214:217], v[76:79]
	v_mfma_f32_16x16x32_bf16 v[72:75], v[136:139], v[214:217], v[72:75]
	v_mfma_f32_16x16x32_bf16 v[124:127], v[132:135], v[194:197], v[124:127]
	v_mfma_f32_16x16x32_bf16 v[120:123], v[140:143], v[194:197], v[120:123]
	v_mfma_f32_16x16x32_bf16 v[108:111], v[132:135], v[202:205], v[108:111]
	v_mfma_f32_16x16x32_bf16 v[104:107], v[140:143], v[202:205], v[104:107]
	v_mfma_f32_16x16x32_bf16 v[92:95], v[132:135], v[210:213], v[92:95]
	v_mfma_f32_16x16x32_bf16 v[88:91], v[140:143], v[210:213], v[88:91]
	v_mfma_f32_16x16x32_bf16 v[76:79], v[132:135], v[218:221], v[76:79]
	v_mfma_f32_16x16x32_bf16 v[72:75], v[140:143], v[218:221], v[72:75]
	v_mfma_f32_16x16x32_bf16 v[116:119], v[162:165], v[190:193], v[116:119]
	v_mfma_f32_16x16x32_bf16 v[112:115], v[170:173], v[190:193], v[112:115]
	v_mfma_f32_16x16x32_bf16 v[100:103], v[162:165], v[198:201], v[100:103]
	v_mfma_f32_16x16x32_bf16 v[96:99], v[170:173], v[198:201], v[96:99]
	v_mfma_f32_16x16x32_bf16 v[84:87], v[162:165], v[206:209], v[84:87]
	v_mfma_f32_16x16x32_bf16 v[80:83], v[170:173], v[206:209], v[80:83]
	v_mfma_f32_16x16x32_bf16 v[68:71], v[162:165], v[214:217], v[68:71]
	v_mfma_f32_16x16x32_bf16 v[64:67], v[170:173], v[214:217], v[64:67]
	v_mfma_f32_16x16x32_bf16 v[116:119], v[166:169], v[194:197], v[116:119]
	v_mfma_f32_16x16x32_bf16 v[112:115], v[186:189], v[194:197], v[112:115]
	v_mfma_f32_16x16x32_bf16 v[100:103], v[166:169], v[202:205], v[100:103]
	v_mfma_f32_16x16x32_bf16 v[96:99], v[186:189], v[202:205], v[96:99]
	v_mfma_f32_16x16x32_bf16 v[84:87], v[166:169], v[210:213], v[84:87]
	v_mfma_f32_16x16x32_bf16 v[80:83], v[186:189], v[210:213], v[80:83]
	v_mfma_f32_16x16x32_bf16 v[68:71], v[166:169], v[218:221], v[68:71]
	v_mfma_f32_16x16x32_bf16 v[64:67], v[186:189], v[218:221], v[64:67]
	s_barrier
	s_setprio 0
	s_add_u32 s98, s12, s48
	s_addc_u32 s99, s13, s49
	s_add_i32 s6, s38, s84
	s_mov_b32 m0, s6
	ds_read_b128 v[190:193], v181 offset:49152
	ds_read_b128 v[194:197], v181 offset:50176
	ds_read_b128 v[198:201], v181 offset:51200
	ds_read_b128 v[202:205], v181 offset:52224
	ds_read_b128 v[206:209], v181 offset:53248
	ds_read_b128 v[210:213], v181 offset:54272
	ds_read_b128 v[214:217], v181 offset:55296
	ds_read_b128 v[218:221], v181 offset:56320
	global_load_lds_dwordx4 v146, s[98:99]
	s_add_i32 m0, s6, 0x2000
	s_add_u32 s6, s12, 0x40080
	s_addc_u32 s7, s13, 0
	s_add_i32 s12, s39, s84
	global_load_lds_dwordx4 v150, s[98:99]
	s_mov_b32 m0, s12
	s_nop 0
	global_load_lds_dwordx4 v146, s[6:7]
	s_add_i32 m0, s12, 0x2000
	s_nop 0
	global_load_lds_dwordx4 v150, s[6:7]
	s_mov_b32 m0, s33
	s_nop 0
	global_load_lds_dwordx4 v144, s[10:11]
	s_mov_b32 m0, s56
	s_nop 0
	global_load_lds_dwordx4 v148, s[10:11]
	s_waitcnt vmcnt(8)
	s_waitcnt lgkmcnt(0)
	s_setprio 1
	s_barrier
	v_mfma_f32_16x16x32_bf16 v[60:63], v[128:131], v[190:193], v[60:63]
	v_mfma_f32_16x16x32_bf16 v[56:59], v[136:139], v[190:193], v[56:59]
	v_mfma_f32_16x16x32_bf16 v[44:47], v[128:131], v[198:201], v[44:47]
	v_mfma_f32_16x16x32_bf16 v[40:43], v[136:139], v[198:201], v[40:43]
	v_mfma_f32_16x16x32_bf16 v[28:31], v[128:131], v[206:209], v[28:31]
	v_mfma_f32_16x16x32_bf16 v[24:27], v[136:139], v[206:209], v[24:27]
	v_mfma_f32_16x16x32_bf16 v[12:15], v[128:131], v[214:217], v[12:15]
	v_mfma_f32_16x16x32_bf16 v[8:11], v[136:139], v[214:217], v[8:11]
	v_mfma_f32_16x16x32_bf16 v[60:63], v[132:135], v[194:197], v[60:63]
	v_mfma_f32_16x16x32_bf16 v[56:59], v[140:143], v[194:197], v[56:59]
	v_mfma_f32_16x16x32_bf16 v[44:47], v[132:135], v[202:205], v[44:47]
	v_mfma_f32_16x16x32_bf16 v[40:43], v[140:143], v[202:205], v[40:43]
	v_mfma_f32_16x16x32_bf16 v[28:31], v[132:135], v[210:213], v[28:31]
	v_mfma_f32_16x16x32_bf16 v[24:27], v[140:143], v[210:213], v[24:27]
	v_mfma_f32_16x16x32_bf16 v[12:15], v[132:135], v[218:221], v[12:15]
	v_mfma_f32_16x16x32_bf16 v[8:11], v[140:143], v[218:221], v[8:11]
	v_mfma_f32_16x16x32_bf16 v[52:55], v[162:165], v[190:193], v[52:55]
	v_mfma_f32_16x16x32_bf16 v[48:51], v[170:173], v[190:193], v[48:51]
	v_mfma_f32_16x16x32_bf16 v[36:39], v[162:165], v[198:201], v[36:39]
	v_mfma_f32_16x16x32_bf16 v[32:35], v[170:173], v[198:201], v[32:35]
	v_mfma_f32_16x16x32_bf16 v[20:23], v[162:165], v[206:209], v[20:23]
	v_mfma_f32_16x16x32_bf16 v[16:19], v[170:173], v[206:209], v[16:19]
	v_mfma_f32_16x16x32_bf16 v[4:7], v[162:165], v[214:217], v[4:7]
	v_mfma_f32_16x16x32_bf16 v[0:3], v[170:173], v[214:217], v[0:3]
	v_mfma_f32_16x16x32_bf16 v[52:55], v[166:169], v[194:197], v[52:55]
	v_mfma_f32_16x16x32_bf16 v[48:51], v[186:189], v[194:197], v[48:51]
	v_mfma_f32_16x16x32_bf16 v[36:39], v[166:169], v[202:205], v[36:39]
	v_mfma_f32_16x16x32_bf16 v[32:35], v[186:189], v[202:205], v[32:35]
	v_mfma_f32_16x16x32_bf16 v[20:23], v[166:169], v[210:213], v[20:23]
	v_mfma_f32_16x16x32_bf16 v[16:19], v[186:189], v[210:213], v[16:19]
	v_mfma_f32_16x16x32_bf16 v[4:7], v[166:169], v[218:221], v[4:7]
	v_mfma_f32_16x16x32_bf16 v[0:3], v[186:189], v[218:221], v[0:3]
	s_barrier
	s_setprio 0
	s_add_i32 s92, s92, 2
	s_add_u32 vcc_lo, vcc_lo, 0x100
	s_addc_u32 vcc_hi, vcc_hi, 0
	s_cmp_gt_u32 s92, 13
	s_mov_b64 s[6:7], s[8:9]
	s_cbranch_scc0 .LBB0_228
	s_and_b64 vcc, exec, s[82:83]
	s_cbranch_vccz .LBB0_231
	s_barrier

.LBB0_448:
	v_add_u32_e32 v1, s78, v210
	ds_read_b128 v[132:135], v1
	ds_read_b128 v[136:139], v1 offset:1024
	ds_read_b128 v[140:143], v1 offset:2048
	ds_read_b128 v[144:147], v1 offset:3072
	v_add_u32_e32 v1, s79, v210
	s_add_u32 s48, s38, s46
	ds_read_b128 v[148:151], v1
	ds_read_b128 v[152:155], v1 offset:1024
	ds_read_b128 v[156:159], v1 offset:2048
	ds_read_b128 v[160:163], v1 offset:3072
	s_addc_u32 s49, s39, s47
	s_add_u32 s48, s48, 0x10000
	s_addc_u32 s49, s49, 0
	s_cmp_eq_u32 s46, 0xf0000
	s_cselect_b32 s64, s81, s48
	s_cselect_b32 s65, s21, s49
	s_cselect_b32 s50, s83, s41
	s_cselect_b32 s51, s19, s86
	s_add_u32 s48, s64, 0x8000
	s_addc_u32 s49, s65, 0
	v_lshl_add_u64 v[2:3], v[204:205], 0, s[46:47]
	s_add_i32 m0, s35, 0xc000
	ds_read_b128 v[164:167], v211
	ds_read_b128 v[168:171], v211 offset:1024
	ds_read_b128 v[172:175], v211 offset:2048
	ds_read_b128 v[176:179], v211 offset:3072
	ds_read_b128 v[180:183], v211 offset:4096
	ds_read_b128 v[184:187], v211 offset:5120
	ds_read_b128 v[212:215], v211 offset:6144
	ds_read_b128 v[216:219], v211 offset:7168
	global_load_lds_dwordx4 v[2:3], off
	v_lshl_add_u64 v[2:3], v[206:207], 0, s[46:47]
	s_add_i32 m0, s35, 0xe000
	s_nop 0
	global_load_lds_dwordx4 v[2:3], off
	s_waitcnt vmcnt(8)
	s_waitcnt lgkmcnt(0)
	s_setprio 1
	s_barrier
	v_mfma_f32_16x16x32_bf16 v[128:131], v[132:135], v[164:167], v[128:131]
	v_mfma_f32_16x16x32_bf16 v[124:127], v[140:143], v[164:167], v[124:127]
	v_mfma_f32_16x16x32_bf16 v[112:115], v[132:135], v[172:175], v[112:115]
	v_mfma_f32_16x16x32_bf16 v[108:111], v[140:143], v[172:175], v[108:111]
	v_mfma_f32_16x16x32_bf16 v[96:99], v[132:135], v[180:183], v[96:99]
	v_mfma_f32_16x16x32_bf16 v[92:95], v[140:143], v[180:183], v[92:95]
	v_mfma_f32_16x16x32_bf16 v[80:83], v[132:135], v[212:215], v[80:83]
	v_mfma_f32_16x16x32_bf16 v[76:79], v[140:143], v[212:215], v[76:79]
	v_mfma_f32_16x16x32_bf16 v[128:131], v[136:139], v[168:171], v[128:131]
	v_mfma_f32_16x16x32_bf16 v[124:127], v[144:147], v[168:171], v[124:127]
	v_mfma_f32_16x16x32_bf16 v[112:115], v[136:139], v[176:179], v[112:115]
	v_mfma_f32_16x16x32_bf16 v[108:111], v[144:147], v[176:179], v[108:111]
	v_mfma_f32_16x16x32_bf16 v[96:99], v[136:139], v[184:187], v[96:99]
	v_mfma_f32_16x16x32_bf16 v[92:95], v[144:147], v[184:187], v[92:95]
	v_mfma_f32_16x16x32_bf16 v[80:83], v[136:139], v[216:219], v[80:83]
	v_mfma_f32_16x16x32_bf16 v[76:79], v[144:147], v[216:219], v[76:79]
	v_mfma_f32_16x16x32_bf16 v[120:123], v[148:151], v[164:167], v[120:123]
	v_mfma_f32_16x16x32_bf16 v[116:119], v[156:159], v[164:167], v[116:119]
	v_mfma_f32_16x16x32_bf16 v[104:107], v[148:151], v[172:175], v[104:107]
	v_mfma_f32_16x16x32_bf16 v[100:103], v[156:159], v[172:175], v[100:103]
	v_mfma_f32_16x16x32_bf16 v[88:91], v[148:151], v[180:183], v[88:91]
	v_mfma_f32_16x16x32_bf16 v[84:87], v[156:159], v[180:183], v[84:87]
	v_mfma_f32_16x16x32_bf16 v[72:75], v[148:151], v[212:215], v[72:75]
	v_mfma_f32_16x16x32_bf16 v[68:71], v[156:159], v[212:215], v[68:71]
	v_mfma_f32_16x16x32_bf16 v[120:123], v[152:155], v[168:171], v[120:123]
	v_mfma_f32_16x16x32_bf16 v[116:119], v[160:163], v[168:171], v[116:119]
	v_mfma_f32_16x16x32_bf16 v[104:107], v[152:155], v[176:179], v[104:107]
	v_mfma_f32_16x16x32_bf16 v[100:103], v[160:163], v[176:179], v[100:103]
	v_mfma_f32_16x16x32_bf16 v[88:91], v[152:155], v[184:187], v[88:91]
	v_mfma_f32_16x16x32_bf16 v[84:87], v[160:163], v[184:187], v[84:87]
	v_mfma_f32_16x16x32_bf16 v[72:75], v[152:155], v[216:219], v[72:75]
	v_mfma_f32_16x16x32_bf16 v[68:71], v[160:163], v[216:219], v[68:71]
	s_barrier
	s_setprio 0
	s_add_i32 s88, s78, s34
	s_mov_b32 m0, s88
	ds_read_b128 v[164:167], v211 offset:16384
	ds_read_b128 v[168:171], v211 offset:17408
	ds_read_b128 v[172:175], v211 offset:18432
	ds_read_b128 v[176:179], v211 offset:19456
	ds_read_b128 v[180:183], v211 offset:20480
	ds_read_b128 v[184:187], v211 offset:21504
	ds_read_b128 v[212:215], v211 offset:22528
	ds_read_b128 v[216:219], v211 offset:23552
	global_load_lds_dwordx4 v192, s[50:51]
	s_add_i32 m0, s88, 0x2000
	s_add_u32 s88, s50, 0x80000
	v_lshl_add_u64 v[222:223], s[50:51], 0, v[188:189]
	s_addc_u32 s89, s51, 0
	s_add_i32 s90, s79, s34
	global_load_lds_dwordx4 v[222:223], off
	s_mov_b32 m0, s90
	s_nop 0
	global_load_lds_dwordx4 v192, s[88:89]
	s_add_i32 m0, s90, 0x2000
	s_nop 0
	global_load_lds_dwordx4 v188, s[88:89]
	s_mov_b32 m0, s35
	s_nop 0
	global_load_lds_dwordx4 v194, s[64:65]
	s_mov_b32 m0, s56
	s_nop 0
	global_load_lds_dwordx4 v190, s[64:65]
	s_waitcnt vmcnt(8)
	s_waitcnt lgkmcnt(0)
	s_setprio 1
	s_barrier
	v_mfma_f32_16x16x32_bf16 v[64:67], v[132:135], v[164:167], v[64:67]
	v_mfma_f32_16x16x32_bf16 v[60:63], v[140:143], v[164:167], v[60:63]
	v_mfma_f32_16x16x32_bf16 v[48:51], v[132:135], v[172:175], v[48:51]
	v_mfma_f32_16x16x32_bf16 v[44:47], v[140:143], v[172:175], v[44:47]
	v_mfma_f32_16x16x32_bf16 v[32:35], v[132:135], v[180:183], v[32:35]
	v_mfma_f32_16x16x32_bf16 v[28:31], v[140:143], v[180:183], v[28:31]
	v_mfma_f32_16x16x32_bf16 v[16:19], v[132:135], v[212:215], v[16:19]
	v_mfma_f32_16x16x32_bf16 v[12:15], v[140:143], v[212:215], v[12:15]
	v_mfma_f32_16x16x32_bf16 v[64:67], v[136:139], v[168:171], v[64:67]
	v_mfma_f32_16x16x32_bf16 v[60:63], v[144:147], v[168:171], v[60:63]
	v_mfma_f32_16x16x32_bf16 v[48:51], v[136:139], v[176:179], v[48:51]
	v_mfma_f32_16x16x32_bf16 v[44:47], v[144:147], v[176:179], v[44:47]
	v_mfma_f32_16x16x32_bf16 v[32:35], v[136:139], v[184:187], v[32:35]
	v_mfma_f32_16x16x32_bf16 v[28:31], v[144:147], v[184:187], v[28:31]
	v_mfma_f32_16x16x32_bf16 v[16:19], v[136:139], v[216:219], v[16:19]
	v_mfma_f32_16x16x32_bf16 v[12:15], v[144:147], v[216:219], v[12:15]
	v_mfma_f32_16x16x32_bf16 v[56:59], v[148:151], v[164:167], v[56:59]
	v_mfma_f32_16x16x32_bf16 v[52:55], v[156:159], v[164:167], v[52:55]
	v_mfma_f32_16x16x32_bf16 v[40:43], v[148:151], v[172:175], v[40:43]
	v_mfma_f32_16x16x32_bf16 v[36:39], v[156:159], v[172:175], v[36:39]
	v_mfma_f32_16x16x32_bf16 v[24:27], v[148:151], v[180:183], v[24:27]
	v_mfma_f32_16x16x32_bf16 v[20:23], v[156:159], v[180:183], v[20:23]
	v_mfma_f32_16x16x32_bf16 v[8:11], v[148:151], v[212:215], v[8:11]
	v_mfma_f32_16x16x32_bf16 v[2:5], v[156:159], v[212:215], v[4:7]
	v_mfma_f32_16x16x32_bf16 v[56:59], v[152:155], v[168:171], v[56:59]
	v_mfma_f32_16x16x32_bf16 v[52:55], v[160:163], v[168:171], v[52:55]
	v_mfma_f32_16x16x32_bf16 v[40:43], v[152:155], v[176:179], v[40:43]
	v_mfma_f32_16x16x32_bf16 v[36:39], v[160:163], v[176:179], v[36:39]
	v_mfma_f32_16x16x32_bf16 v[24:27], v[152:155], v[184:187], v[24:27]
	v_mfma_f32_16x16x32_bf16 v[20:23], v[160:163], v[184:187], v[20:23]
	v_mfma_f32_16x16x32_bf16 v[8:11], v[152:155], v[216:219], v[8:11]
	v_mfma_f32_16x16x32_bf16 v[2:5], v[160:163], v[216:219], v[2:5]
	s_barrier
	s_setprio 0
	s_add_i32 s88, 0, 0x18000
	v_add_u32_e32 v1, s88, v210
	s_add_i32 s89, 0, 0x1c000
	ds_read_b128 v[132:135], v1
	ds_read_b128 v[136:139], v1 offset:1024
	ds_read_b128 v[140:143], v1 offset:2048
	ds_read_b128 v[144:147], v1 offset:3072
	v_add_u32_e32 v1, s89, v210
	ds_read_b128 v[148:151], v1
	ds_read_b128 v[152:155], v1 offset:1024
	ds_read_b128 v[156:159], v1 offset:2048
	ds_read_b128 v[160:163], v1 offset:3072
	s_add_u32 s64, s64, 0x2000
	s_addc_u32 s65, s65, 0
	s_mov_b32 m0, s57
	ds_read_b128 v[164:167], v211 offset:32768
	ds_read_b128 v[168:171], v211 offset:33792
	ds_read_b128 v[172:175], v211 offset:34816
	ds_read_b128 v[176:179], v211 offset:35840
	ds_read_b128 v[180:183], v211 offset:36864
	ds_read_b128 v[184:187], v211 offset:37888
	ds_read_b128 v[212:215], v211 offset:38912
	ds_read_b128 v[216:219], v211 offset:39936
	global_load_lds_dwordx4 v194, s[64:65]
	s_mov_b32 m0, s59
	s_nop 0
	global_load_lds_dwordx4 v190, s[64:65]
	s_waitcnt vmcnt(8)
	s_waitcnt lgkmcnt(0)
	s_setprio 1
	s_barrier
	v_mfma_f32_16x16x32_bf16 v[128:131], v[132:135], v[164:167], v[128:131]
	v_mfma_f32_16x16x32_bf16 v[124:127], v[140:143], v[164:167], v[124:127]
	v_mfma_f32_16x16x32_bf16 v[112:115], v[132:135], v[172:175], v[112:115]
	v_mfma_f32_16x16x32_bf16 v[108:111], v[140:143], v[172:175], v[108:111]
	v_mfma_f32_16x16x32_bf16 v[96:99], v[132:135], v[180:183], v[96:99]
	v_mfma_f32_16x16x32_bf16 v[92:95], v[140:143], v[180:183], v[92:95]
	v_mfma_f32_16x16x32_bf16 v[80:83], v[132:135], v[212:215], v[80:83]
	v_mfma_f32_16x16x32_bf16 v[76:79], v[140:143], v[212:215], v[76:79]
	v_mfma_f32_16x16x32_bf16 v[128:131], v[136:139], v[168:171], v[128:131]
	v_mfma_f32_16x16x32_bf16 v[124:127], v[144:147], v[168:171], v[124:127]
	v_mfma_f32_16x16x32_bf16 v[112:115], v[136:139], v[176:179], v[112:115]
	v_mfma_f32_16x16x32_bf16 v[108:111], v[144:147], v[176:179], v[108:111]
	v_mfma_f32_16x16x32_bf16 v[96:99], v[136:139], v[184:187], v[96:99]
	v_mfma_f32_16x16x32_bf16 v[92:95], v[144:147], v[184:187], v[92:95]
	v_mfma_f32_16x16x32_bf16 v[80:83], v[136:139], v[216:219], v[80:83]
	v_mfma_f32_16x16x32_bf16 v[76:79], v[144:147], v[216:219], v[76:79]
	v_mfma_f32_16x16x32_bf16 v[120:123], v[148:151], v[164:167], v[120:123]
	v_mfma_f32_16x16x32_bf16 v[116:119], v[156:159], v[164:167], v[116:119]
	v_mfma_f32_16x16x32_bf16 v[104:107], v[148:151], v[172:175], v[104:107]
	v_mfma_f32_16x16x32_bf16 v[100:103], v[156:159], v[172:175], v[100:103]
	v_mfma_f32_16x16x32_bf16 v[88:91], v[148:151], v[180:183], v[88:91]
	v_mfma_f32_16x16x32_bf16 v[84:87], v[156:159], v[180:183], v[84:87]
	v_mfma_f32_16x16x32_bf16 v[72:75], v[148:151], v[212:215], v[72:75]
	v_mfma_f32_16x16x32_bf16 v[68:71], v[156:159], v[212:215], v[68:71]
	v_mfma_f32_16x16x32_bf16 v[120:123], v[152:155], v[168:171], v[120:123]
	v_mfma_f32_16x16x32_bf16 v[116:119], v[160:163], v[168:171], v[116:119]
	v_mfma_f32_16x16x32_bf16 v[104:107], v[152:155], v[176:179], v[104:107]
	v_mfma_f32_16x16x32_bf16 v[100:103], v[160:163], v[176:179], v[100:103]
	v_mfma_f32_16x16x32_bf16 v[88:91], v[152:155], v[184:187], v[88:91]
	v_mfma_f32_16x16x32_bf16 v[84:87], v[160:163], v[184:187], v[84:87]
	v_mfma_f32_16x16x32_bf16 v[72:75], v[152:155], v[216:219], v[72:75]
	v_mfma_f32_16x16x32_bf16 v[68:71], v[160:163], v[216:219], v[68:71]
	s_barrier
	s_setprio 0
	s_add_u32 s98, s50, s10
	s_addc_u32 s99, s51, s11
	s_add_i32 s64, s88, s34
	s_mov_b32 m0, s64
	ds_read_b128 v[164:167], v211 offset:49152
	ds_read_b128 v[168:171], v211 offset:50176
	ds_read_b128 v[172:175], v211 offset:51200
	ds_read_b128 v[176:179], v211 offset:52224
	ds_read_b128 v[180:183], v211 offset:53248
	ds_read_b128 v[184:187], v211 offset:54272
	ds_read_b128 v[212:215], v211 offset:55296
	ds_read_b128 v[216:219], v211 offset:56320
	global_load_lds_dwordx4 v192, s[98:99]
	s_add_i32 m0, s64, 0x2000
	s_add_u32 s50, s50, 0x80080
	v_lshl_add_u64 v[6:7], v[222:223], 0, s[10:11]
	s_addc_u32 s51, s51, 0
	s_add_i32 s64, s89, s34
	global_load_lds_dwordx4 v[6:7], off
	s_mov_b32 m0, s64
	s_nop 0
	global_load_lds_dwordx4 v192, s[50:51]
	s_add_i32 m0, s64, 0x2000
	s_nop 0
	global_load_lds_dwordx4 v188, s[50:51]
	s_mov_b32 m0, s74
	s_nop 0
	global_load_lds_dwordx4 v194, s[48:49]
	s_mov_b32 m0, s75
	s_nop 0
	global_load_lds_dwordx4 v190, s[48:49]
	s_waitcnt vmcnt(8)
	s_waitcnt lgkmcnt(0)
	s_setprio 1
	s_barrier
	v_mfma_f32_16x16x32_bf16 v[64:67], v[132:135], v[164:167], v[64:67]
	v_mfma_f32_16x16x32_bf16 v[60:63], v[140:143], v[164:167], v[60:63]
	v_mfma_f32_16x16x32_bf16 v[48:51], v[132:135], v[172:175], v[48:51]
	v_mfma_f32_16x16x32_bf16 v[44:47], v[140:143], v[172:175], v[44:47]
	v_mfma_f32_16x16x32_bf16 v[32:35], v[132:135], v[180:183], v[32:35]
	v_mfma_f32_16x16x32_bf16 v[28:31], v[140:143], v[180:183], v[28:31]
	v_mfma_f32_16x16x32_bf16 v[16:19], v[132:135], v[212:215], v[16:19]
	v_mfma_f32_16x16x32_bf16 v[12:15], v[140:143], v[212:215], v[12:15]
	v_mfma_f32_16x16x32_bf16 v[64:67], v[136:139], v[168:171], v[64:67]
	v_mfma_f32_16x16x32_bf16 v[60:63], v[144:147], v[168:171], v[60:63]
	v_mfma_f32_16x16x32_bf16 v[48:51], v[136:139], v[176:179], v[48:51]
	v_mfma_f32_16x16x32_bf16 v[44:47], v[144:147], v[176:179], v[44:47]
	v_mfma_f32_16x16x32_bf16 v[32:35], v[136:139], v[184:187], v[32:35]
	v_mfma_f32_16x16x32_bf16 v[28:31], v[144:147], v[184:187], v[28:31]
	v_mfma_f32_16x16x32_bf16 v[16:19], v[136:139], v[216:219], v[16:19]
	v_mfma_f32_16x16x32_bf16 v[12:15], v[144:147], v[216:219], v[12:15]
	v_mfma_f32_16x16x32_bf16 v[56:59], v[148:151], v[164:167], v[56:59]
	v_mfma_f32_16x16x32_bf16 v[52:55], v[156:159], v[164:167], v[52:55]
	v_mfma_f32_16x16x32_bf16 v[40:43], v[148:151], v[172:175], v[40:43]
	v_mfma_f32_16x16x32_bf16 v[36:39], v[156:159], v[172:175], v[36:39]
	v_mfma_f32_16x16x32_bf16 v[24:27], v[148:151], v[180:183], v[24:27]
	v_mfma_f32_16x16x32_bf16 v[20:23], v[156:159], v[180:183], v[20:23]
	v_mfma_f32_16x16x32_bf16 v[6:9], v[148:151], v[212:215], v[8:11]
	v_mfma_f32_16x16x32_bf16 v[2:5], v[156:159], v[212:215], v[2:5]
	v_mfma_f32_16x16x32_bf16 v[56:59], v[152:155], v[168:171], v[56:59]
	v_mfma_f32_16x16x32_bf16 v[52:55], v[160:163], v[168:171], v[52:55]
	v_mfma_f32_16x16x32_bf16 v[40:43], v[152:155], v[176:179], v[40:43]
	v_mfma_f32_16x16x32_bf16 v[36:39], v[160:163], v[176:179], v[36:39]
	v_mfma_f32_16x16x32_bf16 v[24:27], v[152:155], v[184:187], v[24:27]
	v_mfma_f32_16x16x32_bf16 v[20:23], v[160:163], v[184:187], v[20:23]
	v_mfma_f32_16x16x32_bf16 v[8:11], v[152:155], v[216:219], v[6:9]
	v_mfma_f32_16x16x32_bf16 v[4:7], v[160:163], v[216:219], v[2:5]
	s_barrier
	s_setprio 0
	s_add_i32 s87, s87, 2
	s_add_u32 s41, s41, 0x100
	s_addc_u32 s86, s86, 0
	s_add_u32 s46, s46, 0x10000
	s_addc_u32 s47, s47, 0
	s_cmp_gt_u32 s87, 29
	s_cbranch_scc1 .LBB0_440

.LBB0_507:
	ds_read_b128 v[128:131], v229
	ds_read_b128 v[132:135], v229 offset:1024
	ds_read_b128 v[136:139], v229 offset:2048
	ds_read_b128 v[140:143], v229 offset:3072
	ds_read_b128 v[144:147], v230
	ds_read_b128 v[148:151], v230 offset:1024
	ds_read_b128 v[152:155], v230 offset:2048
	ds_read_b128 v[156:159], v230 offset:3072
	s_add_u32 s44, s42, 0x10000
	s_addc_u32 s45, s43, 0
	s_cmp_eq_u32 s83, 12
	s_cselect_b32 s50, s21, s44
	s_cselect_b32 s51, s8, s45
	s_cselect_b32 s48, s29, s80
	s_cselect_b32 s49, s27, s81
	s_add_u32 s46, s50, 0x8000
	s_addc_u32 s47, s51, 0
	s_add_i32 m0, s23, 0xc000
	ds_read_b128 v[160:163], v231
	ds_read_b128 v[164:167], v231 offset:1024
	ds_read_b128 v[168:171], v231 offset:2048
	ds_read_b128 v[172:175], v231 offset:3072
	ds_read_b128 v[176:179], v231 offset:4096
	ds_read_b128 v[180:183], v231 offset:5120
	ds_read_b128 v[184:187], v231 offset:6144
	ds_read_b128 v[188:191], v231 offset:7168
	global_load_lds_dwordx4 v200, s[42:43]
	s_add_i32 m0, s23, 0xe000
	s_nop 0
	global_load_lds_dwordx4 v202, s[42:43]
	s_waitcnt vmcnt(8)
	s_waitcnt lgkmcnt(0)
	s_setprio 1
	s_barrier
	v_mfma_f32_16x16x32_bf16 v[124:127], v[128:131], v[160:163], v[124:127]
	v_mfma_f32_16x16x32_bf16 v[120:123], v[136:139], v[160:163], v[120:123]
	v_mfma_f32_16x16x32_bf16 v[108:111], v[128:131], v[168:171], v[108:111]
	v_mfma_f32_16x16x32_bf16 v[104:107], v[136:139], v[168:171], v[104:107]
	v_mfma_f32_16x16x32_bf16 v[92:95], v[128:131], v[176:179], v[92:95]
	v_mfma_f32_16x16x32_bf16 v[88:91], v[136:139], v[176:179], v[88:91]
	v_mfma_f32_16x16x32_bf16 v[76:79], v[128:131], v[184:187], v[76:79]
	v_mfma_f32_16x16x32_bf16 v[72:75], v[136:139], v[184:187], v[72:75]
	v_mfma_f32_16x16x32_bf16 v[124:127], v[132:135], v[164:167], v[124:127]
	v_mfma_f32_16x16x32_bf16 v[120:123], v[140:143], v[164:167], v[120:123]
	v_mfma_f32_16x16x32_bf16 v[108:111], v[132:135], v[172:175], v[108:111]
	v_mfma_f32_16x16x32_bf16 v[104:107], v[140:143], v[172:175], v[104:107]
	v_mfma_f32_16x16x32_bf16 v[92:95], v[132:135], v[180:183], v[92:95]
	v_mfma_f32_16x16x32_bf16 v[88:91], v[140:143], v[180:183], v[88:91]
	v_mfma_f32_16x16x32_bf16 v[76:79], v[132:135], v[188:191], v[76:79]
	v_mfma_f32_16x16x32_bf16 v[72:75], v[140:143], v[188:191], v[72:75]
	v_mfma_f32_16x16x32_bf16 v[116:119], v[144:147], v[160:163], v[116:119]
	v_mfma_f32_16x16x32_bf16 v[112:115], v[152:155], v[160:163], v[112:115]
	v_mfma_f32_16x16x32_bf16 v[100:103], v[144:147], v[168:171], v[100:103]
	v_mfma_f32_16x16x32_bf16 v[96:99], v[152:155], v[168:171], v[96:99]
	v_mfma_f32_16x16x32_bf16 v[84:87], v[144:147], v[176:179], v[84:87]
	v_mfma_f32_16x16x32_bf16 v[80:83], v[152:155], v[176:179], v[80:83]
	v_mfma_f32_16x16x32_bf16 v[68:71], v[144:147], v[184:187], v[68:71]
	v_mfma_f32_16x16x32_bf16 v[64:67], v[152:155], v[184:187], v[64:67]
	v_mfma_f32_16x16x32_bf16 v[116:119], v[148:151], v[164:167], v[116:119]
	v_mfma_f32_16x16x32_bf16 v[112:115], v[156:159], v[164:167], v[112:115]
	v_mfma_f32_16x16x32_bf16 v[100:103], v[148:151], v[172:175], v[100:103]
	v_mfma_f32_16x16x32_bf16 v[96:99], v[156:159], v[172:175], v[96:99]
	v_mfma_f32_16x16x32_bf16 v[84:87], v[148:151], v[180:183], v[84:87]
	v_mfma_f32_16x16x32_bf16 v[80:83], v[156:159], v[180:183], v[80:83]
	v_mfma_f32_16x16x32_bf16 v[68:71], v[148:151], v[188:191], v[68:71]
	v_mfma_f32_16x16x32_bf16 v[64:67], v[156:159], v[188:191], v[64:67]
	s_barrier
	s_setprio 0
	s_add_i32 s42, s77, s35
	s_mov_b32 m0, s42
	ds_read_b128 v[160:163], v231 offset:16384
	ds_read_b128 v[164:167], v231 offset:17408
	ds_read_b128 v[168:171], v231 offset:18432
	ds_read_b128 v[172:175], v231 offset:19456
	ds_read_b128 v[176:179], v231 offset:20480
	ds_read_b128 v[180:183], v231 offset:21504
	ds_read_b128 v[184:187], v231 offset:22528
	ds_read_b128 v[188:191], v231 offset:23552
	global_load_lds_dwordx4 v194, s[48:49]
	s_add_i32 m0, s42, 0x2000
	s_add_u32 s42, s48, 0x40000
	s_addc_u32 s43, s49, 0
	s_add_i32 s84, s78, s35
	global_load_lds_dwordx4 v198, s[48:49]
	s_mov_b32 m0, s84
	s_nop 0
	global_load_lds_dwordx4 v194, s[42:43]
	s_add_i32 m0, s84, 0x2000
	s_nop 0
	global_load_lds_dwordx4 v198, s[42:43]
	s_mov_b32 m0, s23
	s_nop 0
	global_load_lds_dwordx4 v192, s[50:51]
	s_mov_b32 m0, s56
	s_nop 0
	global_load_lds_dwordx4 v196, s[50:51]
	s_waitcnt vmcnt(8)
	s_waitcnt lgkmcnt(0)
	s_setprio 1
	s_barrier
	v_mfma_f32_16x16x32_bf16 v[60:63], v[128:131], v[160:163], v[60:63]
	v_mfma_f32_16x16x32_bf16 v[56:59], v[136:139], v[160:163], v[56:59]
	v_mfma_f32_16x16x32_bf16 v[44:47], v[128:131], v[168:171], v[44:47]
	v_mfma_f32_16x16x32_bf16 v[40:43], v[136:139], v[168:171], v[40:43]
	v_mfma_f32_16x16x32_bf16 v[28:31], v[128:131], v[176:179], v[28:31]
	v_mfma_f32_16x16x32_bf16 v[24:27], v[136:139], v[176:179], v[24:27]
	v_mfma_f32_16x16x32_bf16 v[12:15], v[128:131], v[184:187], v[12:15]
	v_mfma_f32_16x16x32_bf16 v[8:11], v[136:139], v[184:187], v[8:11]
	v_mfma_f32_16x16x32_bf16 v[60:63], v[132:135], v[164:167], v[60:63]
	v_mfma_f32_16x16x32_bf16 v[56:59], v[140:143], v[164:167], v[56:59]
	v_mfma_f32_16x16x32_bf16 v[44:47], v[132:135], v[172:175], v[44:47]
	v_mfma_f32_16x16x32_bf16 v[40:43], v[140:143], v[172:175], v[40:43]
	v_mfma_f32_16x16x32_bf16 v[28:31], v[132:135], v[180:183], v[28:31]
	v_mfma_f32_16x16x32_bf16 v[24:27], v[140:143], v[180:183], v[24:27]
	v_mfma_f32_16x16x32_bf16 v[12:15], v[132:135], v[188:191], v[12:15]
	v_mfma_f32_16x16x32_bf16 v[8:11], v[140:143], v[188:191], v[8:11]
	v_mfma_f32_16x16x32_bf16 v[52:55], v[144:147], v[160:163], v[52:55]
	v_mfma_f32_16x16x32_bf16 v[48:51], v[152:155], v[160:163], v[48:51]
	v_mfma_f32_16x16x32_bf16 v[36:39], v[144:147], v[168:171], v[36:39]
	v_mfma_f32_16x16x32_bf16 v[32:35], v[152:155], v[168:171], v[32:35]
	v_mfma_f32_16x16x32_bf16 v[20:23], v[144:147], v[176:179], v[20:23]
	v_mfma_f32_16x16x32_bf16 v[16:19], v[152:155], v[176:179], v[16:19]
	v_mfma_f32_16x16x32_bf16 v[4:7], v[144:147], v[184:187], v[4:7]
	v_mfma_f32_16x16x32_bf16 v[0:3], v[152:155], v[184:187], v[0:3]
	v_mfma_f32_16x16x32_bf16 v[52:55], v[148:151], v[164:167], v[52:55]
	v_mfma_f32_16x16x32_bf16 v[48:51], v[156:159], v[164:167], v[48:51]
	v_mfma_f32_16x16x32_bf16 v[36:39], v[148:151], v[172:175], v[36:39]
	v_mfma_f32_16x16x32_bf16 v[32:35], v[156:159], v[172:175], v[32:35]
	v_mfma_f32_16x16x32_bf16 v[20:23], v[148:151], v[180:183], v[20:23]
	v_mfma_f32_16x16x32_bf16 v[16:19], v[156:159], v[180:183], v[16:19]
	v_mfma_f32_16x16x32_bf16 v[4:7], v[148:151], v[188:191], v[4:7]
	v_mfma_f32_16x16x32_bf16 v[0:3], v[156:159], v[188:191], v[0:3]
	s_barrier
	s_setprio 0
	s_add_i32 s84, 0, 0x18000
	s_add_i32 s85, 0, 0x1c000
	v_add_u32_e32 v140, s84, v228
	v_add_u32_e32 v156, s85, v228
	ds_read_b128 v[128:131], v140
	ds_read_b128 v[132:135], v140 offset:1024
	ds_read_b128 v[136:139], v140 offset:2048
	ds_read_b128 v[140:143], v140 offset:3072
	ds_read_b128 v[144:147], v156
	ds_read_b128 v[148:151], v156 offset:1024
	ds_read_b128 v[152:155], v156 offset:2048
	ds_read_b128 v[156:159], v156 offset:3072
	s_add_u32 s42, s50, 0x2000
	s_addc_u32 s43, s51, 0
	s_mov_b32 m0, s57
	ds_read_b128 v[160:163], v231 offset:32768
	ds_read_b128 v[164:167], v231 offset:33792
	ds_read_b128 v[168:171], v231 offset:34816
	ds_read_b128 v[172:175], v231 offset:35840
	ds_read_b128 v[176:179], v231 offset:36864
	ds_read_b128 v[180:183], v231 offset:37888
	ds_read_b128 v[184:187], v231 offset:38912
	ds_read_b128 v[188:191], v231 offset:39936
	global_load_lds_dwordx4 v192, s[42:43]
	s_mov_b32 m0, s59
	s_nop 0
	global_load_lds_dwordx4 v196, s[42:43]
	s_waitcnt vmcnt(8)
	s_waitcnt lgkmcnt(0)
	s_setprio 1
	s_barrier
	v_mfma_f32_16x16x32_bf16 v[124:127], v[128:131], v[160:163], v[124:127]
	v_mfma_f32_16x16x32_bf16 v[120:123], v[136:139], v[160:163], v[120:123]
	v_mfma_f32_16x16x32_bf16 v[108:111], v[128:131], v[168:171], v[108:111]
	v_mfma_f32_16x16x32_bf16 v[104:107], v[136:139], v[168:171], v[104:107]
	v_mfma_f32_16x16x32_bf16 v[92:95], v[128:131], v[176:179], v[92:95]
	v_mfma_f32_16x16x32_bf16 v[88:91], v[136:139], v[176:179], v[88:91]
	v_mfma_f32_16x16x32_bf16 v[76:79], v[128:131], v[184:187], v[76:79]
	v_mfma_f32_16x16x32_bf16 v[72:75], v[136:139], v[184:187], v[72:75]
	v_mfma_f32_16x16x32_bf16 v[124:127], v[132:135], v[164:167], v[124:127]
	v_mfma_f32_16x16x32_bf16 v[120:123], v[140:143], v[164:167], v[120:123]
	v_mfma_f32_16x16x32_bf16 v[108:111], v[132:135], v[172:175], v[108:111]
	v_mfma_f32_16x16x32_bf16 v[104:107], v[140:143], v[172:175], v[104:107]
	v_mfma_f32_16x16x32_bf16 v[92:95], v[132:135], v[180:183], v[92:95]
	v_mfma_f32_16x16x32_bf16 v[88:91], v[140:143], v[180:183], v[88:91]
	v_mfma_f32_16x16x32_bf16 v[76:79], v[132:135], v[188:191], v[76:79]
	v_mfma_f32_16x16x32_bf16 v[72:75], v[140:143], v[188:191], v[72:75]
	v_mfma_f32_16x16x32_bf16 v[116:119], v[144:147], v[160:163], v[116:119]
	v_mfma_f32_16x16x32_bf16 v[112:115], v[152:155], v[160:163], v[112:115]
	v_mfma_f32_16x16x32_bf16 v[100:103], v[144:147], v[168:171], v[100:103]
	v_mfma_f32_16x16x32_bf16 v[96:99], v[152:155], v[168:171], v[96:99]
	v_mfma_f32_16x16x32_bf16 v[84:87], v[144:147], v[176:179], v[84:87]
	v_mfma_f32_16x16x32_bf16 v[80:83], v[152:155], v[176:179], v[80:83]
	v_mfma_f32_16x16x32_bf16 v[68:71], v[144:147], v[184:187], v[68:71]
	v_mfma_f32_16x16x32_bf16 v[64:67], v[152:155], v[184:187], v[64:67]
	v_mfma_f32_16x16x32_bf16 v[116:119], v[148:151], v[164:167], v[116:119]
	v_mfma_f32_16x16x32_bf16 v[112:115], v[156:159], v[164:167], v[112:115]
	v_mfma_f32_16x16x32_bf16 v[100:103], v[148:151], v[172:175], v[100:103]
	v_mfma_f32_16x16x32_bf16 v[96:99], v[156:159], v[172:175], v[96:99]
	v_mfma_f32_16x16x32_bf16 v[84:87], v[148:151], v[180:183], v[84:87]
	v_mfma_f32_16x16x32_bf16 v[80:83], v[156:159], v[180:183], v[80:83]
	v_mfma_f32_16x16x32_bf16 v[68:71], v[148:151], v[188:191], v[68:71]
	v_mfma_f32_16x16x32_bf16 v[64:67], v[156:159], v[188:191], v[64:67]
	s_barrier
	s_setprio 0
	s_add_u32 s98, s48, s16
	s_addc_u32 s99, s49, s17
	s_add_i32 s42, s84, s35
	s_mov_b32 m0, s42
	ds_read_b128 v[160:163], v231 offset:49152
	ds_read_b128 v[164:167], v231 offset:50176
	ds_read_b128 v[168:171], v231 offset:51200
	ds_read_b128 v[172:175], v231 offset:52224
	ds_read_b128 v[176:179], v231 offset:53248
	ds_read_b128 v[180:183], v231 offset:54272
	ds_read_b128 v[184:187], v231 offset:55296
	ds_read_b128 v[188:191], v231 offset:56320
	global_load_lds_dwordx4 v194, s[98:99]
	s_add_i32 m0, s42, 0x2000
	s_add_u32 s42, s48, 0x40080
	s_addc_u32 s43, s49, 0
	s_add_i32 s48, s85, s35
	global_load_lds_dwordx4 v198, s[98:99]
	s_mov_b32 m0, s48
	s_nop 0
	global_load_lds_dwordx4 v194, s[42:43]
	s_add_i32 m0, s48, 0x2000
	s_nop 0
	global_load_lds_dwordx4 v198, s[42:43]
	s_mov_b32 m0, s75
	s_nop 0
	global_load_lds_dwordx4 v192, s[46:47]
	s_mov_b32 m0, s76
	s_nop 0
	global_load_lds_dwordx4 v196, s[46:47]
	s_waitcnt vmcnt(8)
	s_waitcnt lgkmcnt(0)
	s_setprio 1
	s_barrier
	v_mfma_f32_16x16x32_bf16 v[60:63], v[128:131], v[160:163], v[60:63]
	v_mfma_f32_16x16x32_bf16 v[56:59], v[136:139], v[160:163], v[56:59]
	v_mfma_f32_16x16x32_bf16 v[44:47], v[128:131], v[168:171], v[44:47]
	v_mfma_f32_16x16x32_bf16 v[40:43], v[136:139], v[168:171], v[40:43]
	v_mfma_f32_16x16x32_bf16 v[28:31], v[128:131], v[176:179], v[28:31]
	v_mfma_f32_16x16x32_bf16 v[24:27], v[136:139], v[176:179], v[24:27]
	v_mfma_f32_16x16x32_bf16 v[12:15], v[128:131], v[184:187], v[12:15]
	v_mfma_f32_16x16x32_bf16 v[8:11], v[136:139], v[184:187], v[8:11]
	v_mfma_f32_16x16x32_bf16 v[60:63], v[132:135], v[164:167], v[60:63]
	v_mfma_f32_16x16x32_bf16 v[56:59], v[140:143], v[164:167], v[56:59]
	v_mfma_f32_16x16x32_bf16 v[44:47], v[132:135], v[172:175], v[44:47]
	v_mfma_f32_16x16x32_bf16 v[40:43], v[140:143], v[172:175], v[40:43]
	v_mfma_f32_16x16x32_bf16 v[28:31], v[132:135], v[180:183], v[28:31]
	v_mfma_f32_16x16x32_bf16 v[24:27], v[140:143], v[180:183], v[24:27]
	v_mfma_f32_16x16x32_bf16 v[12:15], v[132:135], v[188:191], v[12:15]
	v_mfma_f32_16x16x32_bf16 v[8:11], v[140:143], v[188:191], v[8:11]
	v_mfma_f32_16x16x32_bf16 v[52:55], v[144:147], v[160:163], v[52:55]
	v_mfma_f32_16x16x32_bf16 v[48:51], v[152:155], v[160:163], v[48:51]
	v_mfma_f32_16x16x32_bf16 v[36:39], v[144:147], v[168:171], v[36:39]
	v_mfma_f32_16x16x32_bf16 v[32:35], v[152:155], v[168:171], v[32:35]
	v_mfma_f32_16x16x32_bf16 v[20:23], v[144:147], v[176:179], v[20:23]
	v_mfma_f32_16x16x32_bf16 v[16:19], v[152:155], v[176:179], v[16:19]
	v_mfma_f32_16x16x32_bf16 v[4:7], v[144:147], v[184:187], v[4:7]
	v_mfma_f32_16x16x32_bf16 v[0:3], v[152:155], v[184:187], v[0:3]
	v_mfma_f32_16x16x32_bf16 v[52:55], v[148:151], v[164:167], v[52:55]
	v_mfma_f32_16x16x32_bf16 v[48:51], v[156:159], v[164:167], v[48:51]
	v_mfma_f32_16x16x32_bf16 v[36:39], v[148:151], v[172:175], v[36:39]
	v_mfma_f32_16x16x32_bf16 v[32:35], v[156:159], v[172:175], v[32:35]
	v_mfma_f32_16x16x32_bf16 v[20:23], v[148:151], v[180:183], v[20:23]
	v_mfma_f32_16x16x32_bf16 v[16:19], v[156:159], v[180:183], v[16:19]
	v_mfma_f32_16x16x32_bf16 v[4:7], v[148:151], v[188:191], v[4:7]
	v_mfma_f32_16x16x32_bf16 v[0:3], v[156:159], v[188:191], v[0:3]
	s_barrier
	s_setprio 0
	s_add_i32 s83, s83, 2
	s_add_u32 s80, s80, 0x100
	s_addc_u32 s81, s81, 0
	s_cmp_gt_u32 s83, 13
	s_mov_b64 s[42:43], s[44:45]
	s_cbranch_scc0 .LBB0_507
	v_mov_b32_e32 v233, v227
	v_mov_b32_e32 v144, v226
	s_lshl_b32 s8, s22, 8
	s_or_b32 s8, s8, s73
	v_lshlrev_b32_e32 v208, 3, v233
	v_add_u32_e32 v128, s8, v208
	s_lshr_b32 s8, s20, 4
	s_mul_i32 s42, s8, 0x1800
	s_ashr_i32 s43, s42, 31
	s_lshl_b64 s[42:43], s[42:43], 2
	s_add_u32 s42, s69, s42
	v_ashrrev_i32_e32 v129, 31, v128
	v_add_u32_e32 v210, s72, v144
	s_addc_u32 s43, s70, s43
	v_lshlrev_b64 v[212:213], 2, v[128:129]
	v_lshl_add_u32 v216, s20, 8, v210
	v_lshl_add_u64 v[214:215], s[42:43], 0, v[212:213]
	v_ashrrev_i32_e32 v217, 31, v216
	v_add_co_u32_e32 v128, vcc, s65, v214
	v_lshl_add_u64 v[218:219], s[36:37], 0, v[212:213]
	v_lshlrev_b64 v[144:145], 12, v[216:217]
	v_add_u32_e32 v224, 16, v216
	v_lshl_add_u64 v[132:133], v[214:215], 0, s[10:11]
	v_addc_co_u32_e32 v129, vcc, 0, v215, vcc
	v_lshl_add_u64 v[144:145], v[218:219], 0, v[144:145]
	v_ashrrev_i32_e32 v225, 31, v224
	global_load_dwordx4 v[140:143], v[128:129], off nt
	s_nop 0
	global_load_dwordx4 v[128:131], v[132:133], off offset:528 nt
	global_load_dwordx4 v[136:139], v[132:133], off offset:16 nt
	s_nop 0
	global_load_dwordx4 v[132:135], v[132:133], off offset:512 nt
	s_nop 0
	global_load_dwordx4 v[234:237], v[144:145], off offset:16 nt
	global_load_dwordx4 v[238:241], v[144:145], off nt
	global_load_dwordx4 v[242:245], v[144:145], off offset:528 nt
	global_load_dwordx4 v[246:249], v[144:145], off offset:512 nt
	v_lshlrev_b64 v[144:145], 12, v[224:225]
	v_add_u32_e32 v222, 32, v216
	v_lshl_add_u64 v[144:145], v[218:219], 0, v[144:145]
	v_ashrrev_i32_e32 v223, 31, v222
	global_load_dwordx4 v[184:187], v[144:145], off offset:16 nt
	global_load_dwordx4 v[188:191], v[144:145], off nt
	global_load_dwordx4 v[176:179], v[144:145], off offset:528 nt
	global_load_dwordx4 v[180:183], v[144:145], off offset:512 nt
	v_lshlrev_b64 v[144:145], 12, v[222:223]
	v_add_u32_e32 v220, 48, v216
	v_lshl_add_u64 v[144:145], v[218:219], 0, v[144:145]
	v_ashrrev_i32_e32 v221, 31, v220
	global_load_dwordx4 v[168:171], v[144:145], off offset:16 nt
	global_load_dwordx4 v[172:175], v[144:145], off nt
	global_load_dwordx4 v[160:163], v[144:145], off offset:528 nt
	global_load_dwordx4 v[164:167], v[144:145], off offset:512 nt
	v_lshlrev_b64 v[144:145], 12, v[220:221]
	v_lshl_add_u64 v[148:149], v[218:219], 0, v[144:145]
	global_load_dwordx4 v[152:155], v[148:149], off offset:16 nt
	global_load_dwordx4 v[156:159], v[148:149], off nt
	global_load_dwordx4 v[144:147], v[148:149], off offset:528 nt
	s_nop 0
	global_load_dwordx4 v[148:151], v[148:149], off offset:512 nt
	v_and_b32_e32 v211, 64, v232
	v_xor_b32_e32 v209, 16, v232
	v_add_u32_e32 v211, 64, v211
	v_cmp_lt_i32_e32 vcc, v209, v211
	v_xor_b32_e32 v250, 32, v232
	s_lshl_b32 s42, s22, 2
	v_cndmask_b32_e32 v209, v232, v209, vcc
	v_cmp_lt_i32_e32 vcc, v250, v211
	v_lshlrev_b32_e32 v209, 2, v209
	s_ashr_i32 s43, s42, 31
	v_cndmask_b32_e32 v211, v232, v250, vcc
	v_lshlrev_b32_e32 v211, 2, v211
	v_cmp_eq_u32_e32 vcc, 0, v233
	s_waitcnt vmcnt(0)
	v_pk_fma_f32 v[126:127], v[126:127], v[142:143], v[240:241]
	v_pk_fma_f32 v[124:125], v[124:125], v[140:141], v[238:239]
	v_pk_fma_f32 v[120:121], v[120:121], v[136:137], v[234:235]
	v_mul_f32_e32 v233, v125, v125
	v_mul_f32_e32 v234, v127, v127
	v_fmac_f32_e32 v233, v124, v124
	v_fmac_f32_e32 v234, v126, v126
	v_add_f32_e32 v233, v233, v234
	v_mul_f32_e32 v234, v121, v121
	v_pk_fma_f32 v[122:123], v[122:123], v[138:139], v[236:237]
	v_fmac_f32_e32 v234, v120, v120
	v_add_f32_e32 v233, v233, v234
	v_mul_f32_e32 v234, v123, v123
	v_fmac_f32_e32 v234, v122, v122
	v_pk_fma_f32 v[118:119], v[118:119], v[134:135], v[248:249]
	v_pk_fma_f32 v[116:117], v[116:117], v[132:133], v[246:247]
	v_add_f32_e32 v233, v234, v233
	v_mul_f32_e32 v234, v117, v117
	v_mul_f32_e32 v235, v119, v119
	v_pk_fma_f32 v[112:113], v[112:113], v[128:129], v[242:243]
	v_fmac_f32_e32 v234, v116, v116
	v_fmac_f32_e32 v235, v118, v118
	v_add_f32_e32 v234, v234, v235
	v_mul_f32_e32 v235, v113, v113
	v_pk_fma_f32 v[114:115], v[114:115], v[130:131], v[244:245]
	v_fmac_f32_e32 v235, v112, v112
	v_add_f32_e32 v234, v234, v235
	v_mul_f32_e32 v235, v115, v115
	v_fmac_f32_e32 v235, v114, v114
	v_add_f32_e32 v234, v235, v234
	v_add_f32_e32 v233, v233, v234
	ds_bpermute_b32 v234, v209, v233
	s_waitcnt lgkmcnt(0)
	v_add_f32_e32 v233, v233, v234
	ds_bpermute_b32 v234, v211, v233
	s_and_saveexec_b64 s[44:45], vcc
	s_cbranch_execz .LBB0_510
	v_lshlrev_b64 v[236:237], 6, v[216:217]
	v_lshl_add_u64 v[236:237], s[12:13], 0, v[236:237]
	v_lshl_add_u64 v[236:237], s[42:43], 2, v[236:237]
	s_lshl_b32 s8, s71, 2
	v_lshl_add_u64 v[236:237], v[236:237], 0, s[8:9]
	s_waitcnt lgkmcnt(0)
	v_add_f32_e32 v217, v233, v234
	global_store_dword v[236:237], v217, off

.LBB0_568:
	ds_read_b128 v[128:131], v167
	ds_read_b128 v[132:135], v167 offset:1024
	ds_read_b128 v[136:139], v167 offset:2048
	ds_read_b128 v[140:143], v167 offset:3072
	ds_read_b128 v[160:163], v168
	ds_read_b128 v[170:173], v168 offset:1024
	ds_read_b128 v[174:177], v168 offset:2048
	ds_read_b128 v[178:181], v168 offset:3072
	s_add_u32 s36, s28, 0x10000
	s_addc_u32 s37, s29, 0
	s_cmp_eq_u32 s76, 12
	s_cselect_b32 s42, s27, s36
	s_cselect_b32 s43, s19, s37
	s_cselect_b32 s40, s73, s74
	s_cselect_b32 s41, s17, s75
	s_add_u32 s38, s42, 0x8000
	s_addc_u32 s39, s43, 0
	s_add_i32 m0, s44, 0xc000
	ds_read_b128 v[182:185], v169
	ds_read_b128 v[186:189], v169 offset:1024
	ds_read_b128 v[190:193], v169 offset:2048
	ds_read_b128 v[194:197], v169 offset:3072
	ds_read_b128 v[198:201], v169 offset:4096
	ds_read_b128 v[202:205], v169 offset:5120
	ds_read_b128 v[206:209], v169 offset:6144
	ds_read_b128 v[210:213], v169 offset:7168
	global_load_lds_dwordx4 v152, s[28:29]
	s_add_i32 m0, s44, 0xe000
	s_nop 0
	global_load_lds_dwordx4 v154, s[28:29]
	s_waitcnt vmcnt(8)
	s_waitcnt lgkmcnt(0)
	s_setprio 1
	s_barrier
	v_mfma_f32_16x16x32_bf16 v[124:127], v[128:131], v[182:185], v[124:127]
	v_mfma_f32_16x16x32_bf16 v[120:123], v[136:139], v[182:185], v[120:123]
	v_mfma_f32_16x16x32_bf16 v[116:119], v[128:131], v[190:193], v[116:119]
	v_mfma_f32_16x16x32_bf16 v[112:115], v[136:139], v[190:193], v[112:115]
	v_mfma_f32_16x16x32_bf16 v[92:95], v[128:131], v[198:201], v[92:95]
	v_mfma_f32_16x16x32_bf16 v[88:91], v[136:139], v[198:201], v[88:91]
	v_mfma_f32_16x16x32_bf16 v[76:79], v[128:131], v[206:209], v[76:79]
	v_mfma_f32_16x16x32_bf16 v[72:75], v[136:139], v[206:209], v[72:75]
	v_mfma_f32_16x16x32_bf16 v[124:127], v[132:135], v[186:189], v[124:127]
	v_mfma_f32_16x16x32_bf16 v[120:123], v[140:143], v[186:189], v[120:123]
	v_mfma_f32_16x16x32_bf16 v[116:119], v[132:135], v[194:197], v[116:119]
	v_mfma_f32_16x16x32_bf16 v[112:115], v[140:143], v[194:197], v[112:115]
	v_mfma_f32_16x16x32_bf16 v[92:95], v[132:135], v[202:205], v[92:95]
	v_mfma_f32_16x16x32_bf16 v[88:91], v[140:143], v[202:205], v[88:91]
	v_mfma_f32_16x16x32_bf16 v[76:79], v[132:135], v[210:213], v[76:79]
	v_mfma_f32_16x16x32_bf16 v[72:75], v[140:143], v[210:213], v[72:75]
	v_mfma_f32_16x16x32_bf16 v[108:111], v[160:163], v[182:185], v[108:111]
	v_mfma_f32_16x16x32_bf16 v[104:107], v[174:177], v[182:185], v[104:107]
	v_mfma_f32_16x16x32_bf16 v[100:103], v[160:163], v[190:193], v[100:103]
	v_mfma_f32_16x16x32_bf16 v[96:99], v[174:177], v[190:193], v[96:99]
	v_mfma_f32_16x16x32_bf16 v[84:87], v[160:163], v[198:201], v[84:87]
	v_mfma_f32_16x16x32_bf16 v[80:83], v[174:177], v[198:201], v[80:83]
	v_mfma_f32_16x16x32_bf16 v[68:71], v[160:163], v[206:209], v[68:71]
	v_mfma_f32_16x16x32_bf16 v[64:67], v[174:177], v[206:209], v[64:67]
	v_mfma_f32_16x16x32_bf16 v[108:111], v[170:173], v[186:189], v[108:111]
	v_mfma_f32_16x16x32_bf16 v[104:107], v[178:181], v[186:189], v[104:107]
	v_mfma_f32_16x16x32_bf16 v[100:103], v[170:173], v[194:197], v[100:103]
	v_mfma_f32_16x16x32_bf16 v[96:99], v[178:181], v[194:197], v[96:99]
	v_mfma_f32_16x16x32_bf16 v[84:87], v[170:173], v[202:205], v[84:87]
	v_mfma_f32_16x16x32_bf16 v[80:83], v[178:181], v[202:205], v[80:83]
	v_mfma_f32_16x16x32_bf16 v[68:71], v[170:173], v[210:213], v[68:71]
	v_mfma_f32_16x16x32_bf16 v[64:67], v[178:181], v[210:213], v[64:67]
	s_barrier
	s_setprio 0
	s_add_i32 s28, s70, s35
	s_mov_b32 m0, s28
	ds_read_b128 v[182:185], v169 offset:16384
	ds_read_b128 v[186:189], v169 offset:17408
	ds_read_b128 v[190:193], v169 offset:18432
	ds_read_b128 v[194:197], v169 offset:19456
	ds_read_b128 v[198:201], v169 offset:20480
	ds_read_b128 v[202:205], v169 offset:21504
	ds_read_b128 v[206:209], v169 offset:22528
	ds_read_b128 v[210:213], v169 offset:23552
	global_load_lds_dwordx4 v148, s[40:41]
	s_add_i32 m0, s28, 0x2000
	s_add_u32 s28, s40, 0x40000
	s_addc_u32 s29, s41, 0
	s_add_i32 s77, s71, s35
	global_load_lds_dwordx4 v144, s[40:41]
	s_mov_b32 m0, s77
	s_nop 0
	global_load_lds_dwordx4 v148, s[28:29]
	s_add_i32 m0, s77, 0x2000
	s_nop 0
	global_load_lds_dwordx4 v144, s[28:29]
	s_mov_b32 m0, s44
	s_nop 0
	global_load_lds_dwordx4 v150, s[42:43]
	s_mov_b32 m0, s45
	s_nop 0
	global_load_lds_dwordx4 v146, s[42:43]
	s_waitcnt vmcnt(8)
	s_waitcnt lgkmcnt(0)
	s_setprio 1
	s_barrier
	v_mfma_f32_16x16x32_bf16 v[60:63], v[128:131], v[182:185], v[60:63]
	v_mfma_f32_16x16x32_bf16 v[56:59], v[136:139], v[182:185], v[56:59]
	v_mfma_f32_16x16x32_bf16 v[44:47], v[128:131], v[190:193], v[44:47]
	v_mfma_f32_16x16x32_bf16 v[40:43], v[136:139], v[190:193], v[40:43]
	v_mfma_f32_16x16x32_bf16 v[28:31], v[128:131], v[198:201], v[28:31]
	v_mfma_f32_16x16x32_bf16 v[24:27], v[136:139], v[198:201], v[24:27]
	v_mfma_f32_16x16x32_bf16 v[12:15], v[128:131], v[206:209], v[12:15]
	v_mfma_f32_16x16x32_bf16 v[8:11], v[136:139], v[206:209], v[8:11]
	v_mfma_f32_16x16x32_bf16 v[60:63], v[132:135], v[186:189], v[60:63]
	v_mfma_f32_16x16x32_bf16 v[56:59], v[140:143], v[186:189], v[56:59]
	v_mfma_f32_16x16x32_bf16 v[44:47], v[132:135], v[194:197], v[44:47]
	v_mfma_f32_16x16x32_bf16 v[40:43], v[140:143], v[194:197], v[40:43]
	v_mfma_f32_16x16x32_bf16 v[28:31], v[132:135], v[202:205], v[28:31]
	v_mfma_f32_16x16x32_bf16 v[24:27], v[140:143], v[202:205], v[24:27]
	v_mfma_f32_16x16x32_bf16 v[12:15], v[132:135], v[210:213], v[12:15]
	v_mfma_f32_16x16x32_bf16 v[8:11], v[140:143], v[210:213], v[8:11]
	v_mfma_f32_16x16x32_bf16 v[52:55], v[160:163], v[182:185], v[52:55]
	v_mfma_f32_16x16x32_bf16 v[48:51], v[174:177], v[182:185], v[48:51]
	v_mfma_f32_16x16x32_bf16 v[36:39], v[160:163], v[190:193], v[36:39]
	v_mfma_f32_16x16x32_bf16 v[32:35], v[174:177], v[190:193], v[32:35]
	v_mfma_f32_16x16x32_bf16 v[20:23], v[160:163], v[198:201], v[20:23]
	v_mfma_f32_16x16x32_bf16 v[16:19], v[174:177], v[198:201], v[16:19]
	v_mfma_f32_16x16x32_bf16 v[4:7], v[160:163], v[206:209], v[4:7]
	v_mfma_f32_16x16x32_bf16 v[0:3], v[174:177], v[206:209], v[0:3]
	v_mfma_f32_16x16x32_bf16 v[52:55], v[170:173], v[186:189], v[52:55]
	v_mfma_f32_16x16x32_bf16 v[48:51], v[178:181], v[186:189], v[48:51]
	v_mfma_f32_16x16x32_bf16 v[36:39], v[170:173], v[194:197], v[36:39]
	v_mfma_f32_16x16x32_bf16 v[32:35], v[178:181], v[194:197], v[32:35]
	v_mfma_f32_16x16x32_bf16 v[20:23], v[170:173], v[202:205], v[20:23]
	v_mfma_f32_16x16x32_bf16 v[16:19], v[178:181], v[202:205], v[16:19]
	v_mfma_f32_16x16x32_bf16 v[4:7], v[170:173], v[210:213], v[4:7]
	v_mfma_f32_16x16x32_bf16 v[0:3], v[178:181], v[210:213], v[0:3]
	s_barrier
	s_setprio 0
	s_add_i32 s77, 0, 0x18000
	s_add_i32 s78, 0, 0x1c000
	v_add_u32_e32 v140, s77, v166
	v_add_u32_e32 v178, s78, v166
	ds_read_b128 v[128:131], v140
	ds_read_b128 v[132:135], v140 offset:1024
	ds_read_b128 v[136:139], v140 offset:2048
	ds_read_b128 v[140:143], v140 offset:3072
	ds_read_b128 v[160:163], v178
	ds_read_b128 v[170:173], v178 offset:1024
	ds_read_b128 v[174:177], v178 offset:2048
	ds_read_b128 v[178:181], v178 offset:3072
	s_add_u32 s28, s42, 0x2000
	s_addc_u32 s29, s43, 0
	s_mov_b32 m0, s46
	ds_read_b128 v[182:185], v169 offset:32768
	ds_read_b128 v[186:189], v169 offset:33792
	ds_read_b128 v[190:193], v169 offset:34816
	ds_read_b128 v[194:197], v169 offset:35840
	ds_read_b128 v[198:201], v169 offset:36864
	ds_read_b128 v[202:205], v169 offset:37888
	ds_read_b128 v[206:209], v169 offset:38912
	ds_read_b128 v[210:213], v169 offset:39936
	global_load_lds_dwordx4 v150, s[28:29]
	s_mov_b32 m0, s47
	s_nop 0
	global_load_lds_dwordx4 v146, s[28:29]
	s_waitcnt vmcnt(8)
	s_waitcnt lgkmcnt(0)
	s_setprio 1
	s_barrier
	v_mfma_f32_16x16x32_bf16 v[124:127], v[128:131], v[182:185], v[124:127]
	v_mfma_f32_16x16x32_bf16 v[120:123], v[136:139], v[182:185], v[120:123]
	v_mfma_f32_16x16x32_bf16 v[116:119], v[128:131], v[190:193], v[116:119]
	v_mfma_f32_16x16x32_bf16 v[112:115], v[136:139], v[190:193], v[112:115]
	v_mfma_f32_16x16x32_bf16 v[92:95], v[128:131], v[198:201], v[92:95]
	v_mfma_f32_16x16x32_bf16 v[88:91], v[136:139], v[198:201], v[88:91]
	v_mfma_f32_16x16x32_bf16 v[76:79], v[128:131], v[206:209], v[76:79]
	v_mfma_f32_16x16x32_bf16 v[72:75], v[136:139], v[206:209], v[72:75]
	v_mfma_f32_16x16x32_bf16 v[124:127], v[132:135], v[186:189], v[124:127]
	v_mfma_f32_16x16x32_bf16 v[120:123], v[140:143], v[186:189], v[120:123]
	v_mfma_f32_16x16x32_bf16 v[116:119], v[132:135], v[194:197], v[116:119]
	v_mfma_f32_16x16x32_bf16 v[112:115], v[140:143], v[194:197], v[112:115]
	v_mfma_f32_16x16x32_bf16 v[92:95], v[132:135], v[202:205], v[92:95]
	v_mfma_f32_16x16x32_bf16 v[88:91], v[140:143], v[202:205], v[88:91]
	v_mfma_f32_16x16x32_bf16 v[76:79], v[132:135], v[210:213], v[76:79]
	v_mfma_f32_16x16x32_bf16 v[72:75], v[140:143], v[210:213], v[72:75]
	v_mfma_f32_16x16x32_bf16 v[108:111], v[160:163], v[182:185], v[108:111]
	v_mfma_f32_16x16x32_bf16 v[104:107], v[174:177], v[182:185], v[104:107]
	v_mfma_f32_16x16x32_bf16 v[100:103], v[160:163], v[190:193], v[100:103]
	v_mfma_f32_16x16x32_bf16 v[96:99], v[174:177], v[190:193], v[96:99]
	v_mfma_f32_16x16x32_bf16 v[84:87], v[160:163], v[198:201], v[84:87]
	v_mfma_f32_16x16x32_bf16 v[80:83], v[174:177], v[198:201], v[80:83]
	v_mfma_f32_16x16x32_bf16 v[68:71], v[160:163], v[206:209], v[68:71]
	v_mfma_f32_16x16x32_bf16 v[64:67], v[174:177], v[206:209], v[64:67]
	v_mfma_f32_16x16x32_bf16 v[108:111], v[170:173], v[186:189], v[108:111]
	v_mfma_f32_16x16x32_bf16 v[104:107], v[178:181], v[186:189], v[104:107]
	v_mfma_f32_16x16x32_bf16 v[100:103], v[170:173], v[194:197], v[100:103]
	v_mfma_f32_16x16x32_bf16 v[96:99], v[178:181], v[194:197], v[96:99]
	v_mfma_f32_16x16x32_bf16 v[84:87], v[170:173], v[202:205], v[84:87]
	v_mfma_f32_16x16x32_bf16 v[80:83], v[178:181], v[202:205], v[80:83]
	v_mfma_f32_16x16x32_bf16 v[68:71], v[170:173], v[210:213], v[68:71]
	v_mfma_f32_16x16x32_bf16 v[64:67], v[178:181], v[210:213], v[64:67]
	s_barrier
	s_setprio 0
	s_add_u32 s98, s40, s12
	s_addc_u32 s99, s41, s13
	s_add_i32 s28, s77, s35
	s_mov_b32 m0, s28
	ds_read_b128 v[182:185], v169 offset:49152
	ds_read_b128 v[186:189], v169 offset:50176
	ds_read_b128 v[190:193], v169 offset:51200
	ds_read_b128 v[194:197], v169 offset:52224
	ds_read_b128 v[198:201], v169 offset:53248
	ds_read_b128 v[202:205], v169 offset:54272
	ds_read_b128 v[206:209], v169 offset:55296
	ds_read_b128 v[210:213], v169 offset:56320
	global_load_lds_dwordx4 v148, s[98:99]
	s_add_i32 m0, s28, 0x2000
	s_add_u32 s28, s40, 0x40080
	s_addc_u32 s29, s41, 0
	s_add_i32 s40, s78, s35
	global_load_lds_dwordx4 v144, s[98:99]
	s_mov_b32 m0, s40
	s_nop 0
	global_load_lds_dwordx4 v148, s[28:29]
	s_add_i32 m0, s40, 0x2000
	s_nop 0
	global_load_lds_dwordx4 v144, s[28:29]
	s_mov_b32 m0, s68
	s_nop 0
	global_load_lds_dwordx4 v150, s[38:39]
	s_mov_b32 m0, s69
	s_nop 0
	global_load_lds_dwordx4 v146, s[38:39]
	s_waitcnt vmcnt(8)
	s_waitcnt lgkmcnt(0)
	s_setprio 1
	s_barrier
	v_mfma_f32_16x16x32_bf16 v[60:63], v[128:131], v[182:185], v[60:63]
	v_mfma_f32_16x16x32_bf16 v[56:59], v[136:139], v[182:185], v[56:59]
	v_mfma_f32_16x16x32_bf16 v[44:47], v[128:131], v[190:193], v[44:47]
	v_mfma_f32_16x16x32_bf16 v[40:43], v[136:139], v[190:193], v[40:43]
	v_mfma_f32_16x16x32_bf16 v[28:31], v[128:131], v[198:201], v[28:31]
	v_mfma_f32_16x16x32_bf16 v[24:27], v[136:139], v[198:201], v[24:27]
	v_mfma_f32_16x16x32_bf16 v[12:15], v[128:131], v[206:209], v[12:15]
	v_mfma_f32_16x16x32_bf16 v[8:11], v[136:139], v[206:209], v[8:11]
	v_mfma_f32_16x16x32_bf16 v[60:63], v[132:135], v[186:189], v[60:63]
	v_mfma_f32_16x16x32_bf16 v[56:59], v[140:143], v[186:189], v[56:59]
	v_mfma_f32_16x16x32_bf16 v[44:47], v[132:135], v[194:197], v[44:47]
	v_mfma_f32_16x16x32_bf16 v[40:43], v[140:143], v[194:197], v[40:43]
	v_mfma_f32_16x16x32_bf16 v[28:31], v[132:135], v[202:205], v[28:31]
	v_mfma_f32_16x16x32_bf16 v[24:27], v[140:143], v[202:205], v[24:27]
	v_mfma_f32_16x16x32_bf16 v[12:15], v[132:135], v[210:213], v[12:15]
	v_mfma_f32_16x16x32_bf16 v[8:11], v[140:143], v[210:213], v[8:11]
	v_mfma_f32_16x16x32_bf16 v[52:55], v[160:163], v[182:185], v[52:55]
	v_mfma_f32_16x16x32_bf16 v[48:51], v[174:177], v[182:185], v[48:51]
	v_mfma_f32_16x16x32_bf16 v[36:39], v[160:163], v[190:193], v[36:39]
	v_mfma_f32_16x16x32_bf16 v[32:35], v[174:177], v[190:193], v[32:35]
	v_mfma_f32_16x16x32_bf16 v[20:23], v[160:163], v[198:201], v[20:23]
	v_mfma_f32_16x16x32_bf16 v[16:19], v[174:177], v[198:201], v[16:19]
	v_mfma_f32_16x16x32_bf16 v[4:7], v[160:163], v[206:209], v[4:7]
	v_mfma_f32_16x16x32_bf16 v[0:3], v[174:177], v[206:209], v[0:3]
	v_mfma_f32_16x16x32_bf16 v[52:55], v[170:173], v[186:189], v[52:55]
	v_mfma_f32_16x16x32_bf16 v[48:51], v[178:181], v[186:189], v[48:51]
	v_mfma_f32_16x16x32_bf16 v[36:39], v[170:173], v[194:197], v[36:39]
	v_mfma_f32_16x16x32_bf16 v[32:35], v[178:181], v[194:197], v[32:35]
	v_mfma_f32_16x16x32_bf16 v[20:23], v[170:173], v[202:205], v[20:23]
	v_mfma_f32_16x16x32_bf16 v[16:19], v[178:181], v[202:205], v[16:19]
	v_mfma_f32_16x16x32_bf16 v[4:7], v[170:173], v[210:213], v[4:7]
	v_mfma_f32_16x16x32_bf16 v[0:3], v[178:181], v[210:213], v[0:3]
	s_barrier
	s_setprio 0
	s_add_i32 s76, s76, 2
	s_add_u32 s74, s74, 0x100
	s_addc_u32 s75, s75, 0
	s_cmp_gt_u32 s76, 13
	s_mov_b64 s[28:29], s[36:37]
	s_cbranch_scc0 .LBB0_568
	s_and_b64 vcc, exec, s[10:11]
	s_cbranch_vccz .LBB0_571

.LBB0_615:
	v_add_u32_e32 v151, s51, v149
	ds_read_b128 v[152:155], v151
	ds_read_b128 v[156:159], v151 offset:1024
	ds_read_b128 v[160:163], v151 offset:2048
	ds_read_b128 v[164:167], v151 offset:3072
	v_add_u32_e32 v151, s56, v149
	ds_read_b128 v[168:171], v151
	ds_read_b128 v[172:175], v151 offset:1024
	ds_read_b128 v[176:179], v151 offset:2048
	ds_read_b128 v[180:183], v151 offset:3072
	s_add_u32 s38, s12, s36
	s_addc_u32 s39, s13, s37
	s_cmp_eq_u32 s63, 60
	s_cselect_b32 s42, s59, s38
	s_cselect_b32 s43, s23, s39
	s_cselect_b32 s40, s60, s61
	s_cselect_b32 s41, s21, s62
	s_add_u32 s38, s42, 0x8000
	s_addc_u32 s39, s43, 0
	s_add_i32 m0, s44, 0xc000
	ds_read_b128 v[184:187], v150
	ds_read_b128 v[188:191], v150 offset:1024
	ds_read_b128 v[192:195], v150 offset:2048
	ds_read_b128 v[196:199], v150 offset:3072
	ds_read_b128 v[200:203], v150 offset:4096
	ds_read_b128 v[204:207], v150 offset:5120
	ds_read_b128 v[208:211], v150 offset:6144
	ds_read_b128 v[212:215], v150 offset:7168
	global_load_lds_dwordx4 v146, s[12:13]
	s_add_i32 m0, s44, 0xe000
	s_nop 0
	global_load_lds_dwordx4 v144, s[12:13]
	s_waitcnt vmcnt(8)
	s_waitcnt lgkmcnt(0)
	s_setprio 1
	s_barrier
	v_mfma_f32_16x16x32_bf16 v[124:127], v[152:155], v[184:187], v[124:127]
	v_mfma_f32_16x16x32_bf16 v[120:123], v[160:163], v[184:187], v[120:123]
	v_mfma_f32_16x16x32_bf16 v[108:111], v[152:155], v[192:195], v[108:111]
	v_mfma_f32_16x16x32_bf16 v[104:107], v[160:163], v[192:195], v[104:107]
	v_mfma_f32_16x16x32_bf16 v[92:95], v[152:155], v[200:203], v[92:95]
	v_mfma_f32_16x16x32_bf16 v[88:91], v[160:163], v[200:203], v[88:91]
	v_mfma_f32_16x16x32_bf16 v[76:79], v[152:155], v[208:211], v[76:79]
	v_mfma_f32_16x16x32_bf16 v[72:75], v[160:163], v[208:211], v[72:75]
	v_mfma_f32_16x16x32_bf16 v[124:127], v[156:159], v[188:191], v[124:127]
	v_mfma_f32_16x16x32_bf16 v[120:123], v[164:167], v[188:191], v[120:123]
	v_mfma_f32_16x16x32_bf16 v[108:111], v[156:159], v[196:199], v[108:111]
	v_mfma_f32_16x16x32_bf16 v[104:107], v[164:167], v[196:199], v[104:107]
	v_mfma_f32_16x16x32_bf16 v[92:95], v[156:159], v[204:207], v[92:95]
	v_mfma_f32_16x16x32_bf16 v[88:91], v[164:167], v[204:207], v[88:91]
	v_mfma_f32_16x16x32_bf16 v[76:79], v[156:159], v[212:215], v[76:79]
	v_mfma_f32_16x16x32_bf16 v[72:75], v[164:167], v[212:215], v[72:75]
	v_mfma_f32_16x16x32_bf16 v[116:119], v[168:171], v[184:187], v[116:119]
	v_mfma_f32_16x16x32_bf16 v[112:115], v[176:179], v[184:187], v[112:115]
	v_mfma_f32_16x16x32_bf16 v[100:103], v[168:171], v[192:195], v[100:103]
	v_mfma_f32_16x16x32_bf16 v[96:99], v[176:179], v[192:195], v[96:99]
	v_mfma_f32_16x16x32_bf16 v[84:87], v[168:171], v[200:203], v[84:87]
	v_mfma_f32_16x16x32_bf16 v[80:83], v[176:179], v[200:203], v[80:83]
	v_mfma_f32_16x16x32_bf16 v[68:71], v[168:171], v[208:211], v[68:71]
	v_mfma_f32_16x16x32_bf16 v[64:67], v[176:179], v[208:211], v[64:67]
	v_mfma_f32_16x16x32_bf16 v[116:119], v[172:175], v[188:191], v[116:119]
	v_mfma_f32_16x16x32_bf16 v[112:115], v[180:183], v[188:191], v[112:115]
	v_mfma_f32_16x16x32_bf16 v[100:103], v[172:175], v[196:199], v[100:103]
	v_mfma_f32_16x16x32_bf16 v[96:99], v[180:183], v[196:199], v[96:99]
	v_mfma_f32_16x16x32_bf16 v[84:87], v[172:175], v[204:207], v[84:87]
	v_mfma_f32_16x16x32_bf16 v[80:83], v[180:183], v[204:207], v[80:83]
	v_mfma_f32_16x16x32_bf16 v[68:71], v[172:175], v[212:215], v[68:71]
	v_mfma_f32_16x16x32_bf16 v[64:67], v[180:183], v[212:215], v[64:67]
	s_barrier
	s_setprio 0
	s_add_i32 s64, s51, s35
	s_mov_b32 m0, s64
	ds_read_b128 v[184:187], v150 offset:16384
	ds_read_b128 v[188:191], v150 offset:17408
	ds_read_b128 v[192:195], v150 offset:18432
	ds_read_b128 v[196:199], v150 offset:19456
	ds_read_b128 v[200:203], v150 offset:20480
	ds_read_b128 v[204:207], v150 offset:21504
	ds_read_b128 v[208:211], v150 offset:22528
	ds_read_b128 v[212:215], v150 offset:23552
	global_load_lds_dwordx4 v130, s[40:41]
	s_add_i32 m0, s64, 0x2000
	s_add_u32 s64, s40, 0x100000
	v_lshl_add_u64 v[218:219], s[40:41], 0, v[134:135]
	s_addc_u32 s65, s41, 0
	s_add_i32 s66, s56, s35
	global_load_lds_dwordx4 v[218:219], off
	s_mov_b32 m0, s66
	s_nop 0
	global_load_lds_dwordx4 v130, s[64:65]
	s_add_i32 m0, s66, 0x2000
	s_nop 0
	global_load_lds_dwordx4 v134, s[64:65]
	s_mov_b32 m0, s44
	s_nop 0
	global_load_lds_dwordx4 v128, s[42:43]
	s_mov_b32 m0, s45
	s_nop 0
	global_load_lds_dwordx4 v132, s[42:43]
	s_waitcnt vmcnt(8)
	s_waitcnt lgkmcnt(0)
	s_setprio 1
	s_barrier
	v_mfma_f32_16x16x32_bf16 v[60:63], v[152:155], v[184:187], v[60:63]
	v_mfma_f32_16x16x32_bf16 v[56:59], v[160:163], v[184:187], v[56:59]
	v_mfma_f32_16x16x32_bf16 v[44:47], v[152:155], v[192:195], v[44:47]
	v_mfma_f32_16x16x32_bf16 v[40:43], v[160:163], v[192:195], v[40:43]
	v_mfma_f32_16x16x32_bf16 v[28:31], v[152:155], v[200:203], v[28:31]
	v_mfma_f32_16x16x32_bf16 v[24:27], v[160:163], v[200:203], v[24:27]
	v_mfma_f32_16x16x32_bf16 v[12:15], v[152:155], v[208:211], v[12:15]
	v_mfma_f32_16x16x32_bf16 v[8:11], v[160:163], v[208:211], v[8:11]
	v_mfma_f32_16x16x32_bf16 v[60:63], v[156:159], v[188:191], v[60:63]
	v_mfma_f32_16x16x32_bf16 v[56:59], v[164:167], v[188:191], v[56:59]
	v_mfma_f32_16x16x32_bf16 v[44:47], v[156:159], v[196:199], v[44:47]
	v_mfma_f32_16x16x32_bf16 v[40:43], v[164:167], v[196:199], v[40:43]
	v_mfma_f32_16x16x32_bf16 v[28:31], v[156:159], v[204:207], v[28:31]
	v_mfma_f32_16x16x32_bf16 v[24:27], v[164:167], v[204:207], v[24:27]
	v_mfma_f32_16x16x32_bf16 v[12:15], v[156:159], v[212:215], v[12:15]
	v_mfma_f32_16x16x32_bf16 v[8:11], v[164:167], v[212:215], v[8:11]
	v_mfma_f32_16x16x32_bf16 v[52:55], v[168:171], v[184:187], v[52:55]
	v_mfma_f32_16x16x32_bf16 v[48:51], v[176:179], v[184:187], v[48:51]
	v_mfma_f32_16x16x32_bf16 v[36:39], v[168:171], v[192:195], v[36:39]
	v_mfma_f32_16x16x32_bf16 v[32:35], v[176:179], v[192:195], v[32:35]
	v_mfma_f32_16x16x32_bf16 v[20:23], v[168:171], v[200:203], v[20:23]
	v_mfma_f32_16x16x32_bf16 v[16:19], v[176:179], v[200:203], v[16:19]
	v_mfma_f32_16x16x32_bf16 v[4:7], v[168:171], v[208:211], v[4:7]
	v_mfma_f32_16x16x32_bf16 v[0:3], v[176:179], v[208:211], v[0:3]
	v_mfma_f32_16x16x32_bf16 v[52:55], v[172:175], v[188:191], v[52:55]
	v_mfma_f32_16x16x32_bf16 v[48:51], v[180:183], v[188:191], v[48:51]
	v_mfma_f32_16x16x32_bf16 v[36:39], v[172:175], v[196:199], v[36:39]
	v_mfma_f32_16x16x32_bf16 v[32:35], v[180:183], v[196:199], v[32:35]
	v_mfma_f32_16x16x32_bf16 v[20:23], v[172:175], v[204:207], v[20:23]
	v_mfma_f32_16x16x32_bf16 v[16:19], v[180:183], v[204:207], v[16:19]
	v_mfma_f32_16x16x32_bf16 v[4:7], v[172:175], v[212:215], v[4:7]
	v_mfma_f32_16x16x32_bf16 v[0:3], v[180:183], v[212:215], v[0:3]
	s_barrier
	s_setprio 0
	s_add_i32 s64, 0, 0x18000
	v_add_u32_e32 v151, s64, v149
	s_add_i32 s65, 0, 0x1c000
	ds_read_b128 v[152:155], v151
	ds_read_b128 v[156:159], v151 offset:1024
	ds_read_b128 v[160:163], v151 offset:2048
	ds_read_b128 v[164:167], v151 offset:3072
	v_add_u32_e32 v151, s65, v149
	ds_read_b128 v[168:171], v151
	ds_read_b128 v[172:175], v151 offset:1024
	ds_read_b128 v[176:179], v151 offset:2048
	ds_read_b128 v[180:183], v151 offset:3072
	s_add_u32 s42, s42, 0x2000
	s_addc_u32 s43, s43, 0
	s_mov_b32 m0, s46
	ds_read_b128 v[184:187], v150 offset:32768
	ds_read_b128 v[188:191], v150 offset:33792
	ds_read_b128 v[192:195], v150 offset:34816
	ds_read_b128 v[196:199], v150 offset:35840
	ds_read_b128 v[200:203], v150 offset:36864
	ds_read_b128 v[204:207], v150 offset:37888
	ds_read_b128 v[208:211], v150 offset:38912
	ds_read_b128 v[212:215], v150 offset:39936
	global_load_lds_dwordx4 v128, s[42:43]
	s_mov_b32 m0, s47
	s_nop 0
	global_load_lds_dwordx4 v132, s[42:43]
	s_waitcnt vmcnt(8)
	s_waitcnt lgkmcnt(0)
	s_setprio 1
	s_barrier
	v_mfma_f32_16x16x32_bf16 v[124:127], v[152:155], v[184:187], v[124:127]
	v_mfma_f32_16x16x32_bf16 v[120:123], v[160:163], v[184:187], v[120:123]
	v_mfma_f32_16x16x32_bf16 v[108:111], v[152:155], v[192:195], v[108:111]
	v_mfma_f32_16x16x32_bf16 v[104:107], v[160:163], v[192:195], v[104:107]
	v_mfma_f32_16x16x32_bf16 v[92:95], v[152:155], v[200:203], v[92:95]
	v_mfma_f32_16x16x32_bf16 v[88:91], v[160:163], v[200:203], v[88:91]
	v_mfma_f32_16x16x32_bf16 v[76:79], v[152:155], v[208:211], v[76:79]
	v_mfma_f32_16x16x32_bf16 v[72:75], v[160:163], v[208:211], v[72:75]
	v_mfma_f32_16x16x32_bf16 v[124:127], v[156:159], v[188:191], v[124:127]
	v_mfma_f32_16x16x32_bf16 v[120:123], v[164:167], v[188:191], v[120:123]
	v_mfma_f32_16x16x32_bf16 v[108:111], v[156:159], v[196:199], v[108:111]
	v_mfma_f32_16x16x32_bf16 v[104:107], v[164:167], v[196:199], v[104:107]
	v_mfma_f32_16x16x32_bf16 v[92:95], v[156:159], v[204:207], v[92:95]
	v_mfma_f32_16x16x32_bf16 v[88:91], v[164:167], v[204:207], v[88:91]
	v_mfma_f32_16x16x32_bf16 v[76:79], v[156:159], v[212:215], v[76:79]
	v_mfma_f32_16x16x32_bf16 v[72:75], v[164:167], v[212:215], v[72:75]
	v_mfma_f32_16x16x32_bf16 v[116:119], v[168:171], v[184:187], v[116:119]
	v_mfma_f32_16x16x32_bf16 v[112:115], v[176:179], v[184:187], v[112:115]
	v_mfma_f32_16x16x32_bf16 v[100:103], v[168:171], v[192:195], v[100:103]
	v_mfma_f32_16x16x32_bf16 v[96:99], v[176:179], v[192:195], v[96:99]
	v_mfma_f32_16x16x32_bf16 v[84:87], v[168:171], v[200:203], v[84:87]
	v_mfma_f32_16x16x32_bf16 v[80:83], v[176:179], v[200:203], v[80:83]
	v_mfma_f32_16x16x32_bf16 v[68:71], v[168:171], v[208:211], v[68:71]
	v_mfma_f32_16x16x32_bf16 v[64:67], v[176:179], v[208:211], v[64:67]
	v_mfma_f32_16x16x32_bf16 v[116:119], v[172:175], v[188:191], v[116:119]
	v_mfma_f32_16x16x32_bf16 v[112:115], v[180:183], v[188:191], v[112:115]
	v_mfma_f32_16x16x32_bf16 v[100:103], v[172:175], v[196:199], v[100:103]
	v_mfma_f32_16x16x32_bf16 v[96:99], v[180:183], v[196:199], v[96:99]
	v_mfma_f32_16x16x32_bf16 v[84:87], v[172:175], v[204:207], v[84:87]
	v_mfma_f32_16x16x32_bf16 v[80:83], v[180:183], v[204:207], v[80:83]
	v_mfma_f32_16x16x32_bf16 v[68:71], v[172:175], v[212:215], v[68:71]
	v_mfma_f32_16x16x32_bf16 v[64:67], v[180:183], v[212:215], v[64:67]
	s_barrier
	s_setprio 0
	s_add_u32 s98, s40, s16
	s_addc_u32 s99, s41, s17
	s_add_i32 s42, s64, s35
	s_mov_b32 m0, s42
	ds_read_b128 v[184:187], v150 offset:49152
	ds_read_b128 v[188:191], v150 offset:50176
	ds_read_b128 v[192:195], v150 offset:51200
	ds_read_b128 v[196:199], v150 offset:52224
	ds_read_b128 v[200:203], v150 offset:53248
	ds_read_b128 v[204:207], v150 offset:54272
	ds_read_b128 v[208:211], v150 offset:55296
	ds_read_b128 v[212:215], v150 offset:56320
	global_load_lds_dwordx4 v130, s[98:99]
	s_add_i32 m0, s42, 0x2000
	s_add_u32 s40, s40, 0x100080
	v_lshl_add_u64 v[216:217], v[218:219], 0, s[16:17]
	s_addc_u32 s41, s41, 0
	s_add_i32 s42, s65, s35
	global_load_lds_dwordx4 v[216:217], off
	s_mov_b32 m0, s42
	s_nop 0
	global_load_lds_dwordx4 v130, s[40:41]
	s_add_i32 m0, s42, 0x2000
	s_nop 0
	global_load_lds_dwordx4 v134, s[40:41]
	s_mov_b32 m0, s48
	s_nop 0
	global_load_lds_dwordx4 v128, s[38:39]
	s_mov_b32 m0, s49
	s_nop 0
	global_load_lds_dwordx4 v132, s[38:39]
	s_waitcnt vmcnt(8)
	s_waitcnt lgkmcnt(0)
	s_setprio 1
	s_barrier
	v_mfma_f32_16x16x32_bf16 v[60:63], v[152:155], v[184:187], v[60:63]
	v_mfma_f32_16x16x32_bf16 v[56:59], v[160:163], v[184:187], v[56:59]
	v_mfma_f32_16x16x32_bf16 v[44:47], v[152:155], v[192:195], v[44:47]
	v_mfma_f32_16x16x32_bf16 v[40:43], v[160:163], v[192:195], v[40:43]
	v_mfma_f32_16x16x32_bf16 v[28:31], v[152:155], v[200:203], v[28:31]
	v_mfma_f32_16x16x32_bf16 v[24:27], v[160:163], v[200:203], v[24:27]
	v_mfma_f32_16x16x32_bf16 v[12:15], v[152:155], v[208:211], v[12:15]
	v_mfma_f32_16x16x32_bf16 v[8:11], v[160:163], v[208:211], v[8:11]
	v_mfma_f32_16x16x32_bf16 v[60:63], v[156:159], v[188:191], v[60:63]
	v_mfma_f32_16x16x32_bf16 v[56:59], v[164:167], v[188:191], v[56:59]
	v_mfma_f32_16x16x32_bf16 v[44:47], v[156:159], v[196:199], v[44:47]
	v_mfma_f32_16x16x32_bf16 v[40:43], v[164:167], v[196:199], v[40:43]
	v_mfma_f32_16x16x32_bf16 v[28:31], v[156:159], v[204:207], v[28:31]
	v_mfma_f32_16x16x32_bf16 v[24:27], v[164:167], v[204:207], v[24:27]
	v_mfma_f32_16x16x32_bf16 v[12:15], v[156:159], v[212:215], v[12:15]
	v_mfma_f32_16x16x32_bf16 v[8:11], v[164:167], v[212:215], v[8:11]
	v_mfma_f32_16x16x32_bf16 v[52:55], v[168:171], v[184:187], v[52:55]
	v_mfma_f32_16x16x32_bf16 v[48:51], v[176:179], v[184:187], v[48:51]
	v_mfma_f32_16x16x32_bf16 v[36:39], v[168:171], v[192:195], v[36:39]
	v_mfma_f32_16x16x32_bf16 v[32:35], v[176:179], v[192:195], v[32:35]
	v_mfma_f32_16x16x32_bf16 v[20:23], v[168:171], v[200:203], v[20:23]
	v_mfma_f32_16x16x32_bf16 v[16:19], v[176:179], v[200:203], v[16:19]
	v_mfma_f32_16x16x32_bf16 v[4:7], v[168:171], v[208:211], v[4:7]
	v_mfma_f32_16x16x32_bf16 v[0:3], v[176:179], v[208:211], v[0:3]
	v_mfma_f32_16x16x32_bf16 v[52:55], v[172:175], v[188:191], v[52:55]
	v_mfma_f32_16x16x32_bf16 v[48:51], v[180:183], v[188:191], v[48:51]
	v_mfma_f32_16x16x32_bf16 v[36:39], v[172:175], v[196:199], v[36:39]
	v_mfma_f32_16x16x32_bf16 v[32:35], v[180:183], v[196:199], v[32:35]
	v_mfma_f32_16x16x32_bf16 v[20:23], v[172:175], v[204:207], v[20:23]
	v_mfma_f32_16x16x32_bf16 v[16:19], v[180:183], v[204:207], v[16:19]
	v_mfma_f32_16x16x32_bf16 v[4:7], v[172:175], v[212:215], v[4:7]
	v_mfma_f32_16x16x32_bf16 v[0:3], v[180:183], v[212:215], v[0:3]
	s_barrier
	s_setprio 0
	s_add_i32 s63, s63, 2
	s_add_u32 s61, s61, 0x100
	s_addc_u32 s62, s62, 0
	s_add_u32 s36, s36, 0x10000
	s_addc_u32 s37, s37, 0
	v_lshl_add_u64 v[146:147], v[146:147], 0, s[18:19]
	s_cmp_gt_u32 s63, 61
	v_lshl_add_u64 v[144:145], v[144:145], 0, s[18:19]
	s_cbranch_scc0 .LBB0_615
	s_andn2_b64 vcc, exec, s[4:5]
	s_cbranch_vccnz .LBB0_607
	v_mov_b32_e32 v0, 0
	s_mov_b32 s8, s20
	s_mov_b32 s6, s22
	s_mov_b64 s[10:11], s[28:29]
	s_mov_b64 s[12:13], s[26:27]
	s_mov_b32 s50, s57
	v_mov_b32_e32 v1, v0
	v_mov_b32_e32 v2, v0
	v_mov_b32_e32 v3, v0
	v_mov_b32_e32 v4, v0
	v_mov_b32_e32 v5, v0
	v_mov_b32_e32 v6, v0
	v_mov_b32_e32 v7, v0
	v_mov_b32_e32 v16, v0
	v_mov_b32_e32 v17, v0
	v_mov_b32_e32 v18, v0
	v_mov_b32_e32 v19, v0
	v_mov_b32_e32 v20, v0
	v_mov_b32_e32 v21, v0
	v_mov_b32_e32 v22, v0
	v_mov_b32_e32 v23, v0
	v_mov_b32_e32 v32, v0
	v_mov_b32_e32 v33, v0
	v_mov_b32_e32 v34, v0
	v_mov_b32_e32 v35, v0
	v_mov_b32_e32 v36, v0
	v_mov_b32_e32 v37, v0
	v_mov_b32_e32 v38, v0
	v_mov_b32_e32 v39, v0
	v_mov_b32_e32 v48, v0
	v_mov_b32_e32 v49, v0
	v_mov_b32_e32 v50, v0
	v_mov_b32_e32 v51, v0
	v_mov_b32_e32 v52, v0
	v_mov_b32_e32 v53, v0
	v_mov_b32_e32 v54, v0
	v_mov_b32_e32 v55, v0
	v_mov_b32_e32 v8, v0
	v_mov_b32_e32 v9, v0
	v_mov_b32_e32 v10, v0
	v_mov_b32_e32 v11, v0
	v_mov_b32_e32 v12, v0
	v_mov_b32_e32 v13, v0
	v_mov_b32_e32 v14, v0
	v_mov_b32_e32 v15, v0
	v_mov_b32_e32 v24, v0
	v_mov_b32_e32 v25, v0
	v_mov_b32_e32 v26, v0
	v_mov_b32_e32 v27, v0
	v_mov_b32_e32 v28, v0
	v_mov_b32_e32 v29, v0
	v_mov_b32_e32 v30, v0
	v_mov_b32_e32 v31, v0
	v_mov_b32_e32 v40, v0
	v_mov_b32_e32 v41, v0
	v_mov_b32_e32 v42, v0
	v_mov_b32_e32 v43, v0
	v_mov_b32_e32 v44, v0
	v_mov_b32_e32 v45, v0
	v_mov_b32_e32 v46, v0
	v_mov_b32_e32 v47, v0
	v_mov_b32_e32 v56, v0
	v_mov_b32_e32 v57, v0
	v_mov_b32_e32 v58, v0
	v_mov_b32_e32 v59, v0
	v_mov_b32_e32 v60, v0
	v_mov_b32_e32 v61, v0
	v_mov_b32_e32 v62, v0
	v_mov_b32_e32 v63, v0
	v_mov_b32_e32 v64, v0
	v_mov_b32_e32 v65, v0
	v_mov_b32_e32 v66, v0
	v_mov_b32_e32 v67, v0
	v_mov_b32_e32 v68, v0
	v_mov_b32_e32 v69, v0
	v_mov_b32_e32 v70, v0
	v_mov_b32_e32 v71, v0
	v_mov_b32_e32 v80, v0
	v_mov_b32_e32 v81, v0
	v_mov_b32_e32 v82, v0
	v_mov_b32_e32 v83, v0
	v_mov_b32_e32 v84, v0
	v_mov_b32_e32 v85, v0
	v_mov_b32_e32 v86, v0
	v_mov_b32_e32 v87, v0
	v_mov_b32_e32 v96, v0
	v_mov_b32_e32 v97, v0
	v_mov_b32_e32 v98, v0
	v_mov_b32_e32 v99, v0
	v_mov_b32_e32 v100, v0
	v_mov_b32_e32 v101, v0
	v_mov_b32_e32 v102, v0
	v_mov_b32_e32 v103, v0
	v_mov_b32_e32 v112, v0
	v_mov_b32_e32 v113, v0
	v_mov_b32_e32 v114, v0
	v_mov_b32_e32 v115, v0
	v_mov_b32_e32 v116, v0
	v_mov_b32_e32 v117, v0
	v_mov_b32_e32 v118, v0
	v_mov_b32_e32 v119, v0
	v_mov_b32_e32 v72, v0
	v_mov_b32_e32 v73, v0
	v_mov_b32_e32 v74, v0
	v_mov_b32_e32 v75, v0
	v_mov_b32_e32 v76, v0
	v_mov_b32_e32 v77, v0
	v_mov_b32_e32 v78, v0
	v_mov_b32_e32 v79, v0
	v_mov_b32_e32 v88, v0
	v_mov_b32_e32 v89, v0
	v_mov_b32_e32 v90, v0
	v_mov_b32_e32 v91, v0
	v_mov_b32_e32 v92, v0
	v_mov_b32_e32 v93, v0
	v_mov_b32_e32 v94, v0
	v_mov_b32_e32 v95, v0
	v_mov_b32_e32 v104, v0
	v_mov_b32_e32 v105, v0
	v_mov_b32_e32 v106, v0
	v_mov_b32_e32 v107, v0
	v_mov_b32_e32 v108, v0
	v_mov_b32_e32 v109, v0
	v_mov_b32_e32 v110, v0
	v_mov_b32_e32 v111, v0
	v_mov_b32_e32 v120, v0
	v_mov_b32_e32 v121, v0
	v_mov_b32_e32 v122, v0
	v_mov_b32_e32 v123, v0
	v_mov_b32_e32 v124, v0
	v_mov_b32_e32 v125, v0
	v_mov_b32_e32 v126, v0
	v_mov_b32_e32 v127, v0
	s_branch .LBB0_607
